# bit-sliced top-k select with two threshold bits per round (three counts exchanged in one 64-bit LDS atomic): half the barriers, same masks
# speedup vs baseline: 1.0028x; 1.0028x over previous
; DI void a1_task(unsigned char* shm, const bf16_t* prm, const bf16_t* prt, unsigned* mask, int b, int qt, const int tid) {
;     ...
;     unsigned T = 0u;
;     if (qt >= 8) {
;         const int nheld = (qt >= wid) ? ((qt - wid) >> 3) + 1 : 0;
;         bool done = false;
;     ...
;             const unsigned cand = T | (1u << bit);
;             int c = 0;
; #pragma unroll
;             for (int jt = 0; jt < 8; ++jt) {
;                 if (jt < nheld) {
; #pragma unroll
;                     for (int i = 0; i < 16; ++i) c += (key[jt][i] >= cand) ? 1 : 0;
;                 }
;             }
;             c += __shfl_xor(c, 32);
;             if (h == 0 && c) atomicAdd(&cnt[(31 - bit) * 32 + r], (unsigned)c);
;             __syncthreads();
;             const unsigned tot = cnt[(31 - bit) * 32 + r];
;             if (!done) { if (tot >= 256u) T = cand; if (tot == 256u) done = true; }
;             if (__ballot(!done) == 0ull) break;
;         }
;     }
.Lbs_tr_done:
	s_cmp_lt_i32 s41, 8
	s_cselect_b32 s0, 0xffff, -1
	v_mov_b32_e32 v24, s0
	v_mov_b32_e32 v28, 0
	s_cmp_lt_i32 s41, 24
	s_cselect_b32 s0, 0xffff, -1
	v_mov_b32_e32 v25, s0
	v_mov_b32_e32 v29, 0
	s_cmp_lt_i32 s41, 40
	s_cselect_b32 s0, 0xffff, -1
	v_mov_b32_e32 v26, s0
	v_mov_b32_e32 v30, 0
	s_cmp_lt_i32 s41, 56
	s_cselect_b32 s0, 0xffff, -1
	v_mov_b32_e32 v27, s0
	v_mov_b32_e32 v31, 0
	v_mov_b32_e32 v45, 0
	v_lshl_add_u32 v48, v100, 2, v136
	s_movk_i32 s42, 0xff
	s_movk_i32 s43, 0x100
	s_mov_b32 s6, 0xffff
	s_mov_b64 s[44:45], 0
	s_mov_b64 s[46:47], 0
	v_and_b32_e32 v32, v24, v172
	v_bcnt_u32_b32 v42, v32, v45
	v_and_b32_e32 v22, v24, v173
	v_and_b32_e32 v23, v32, v22
	v_bcnt_u32_b32 v43, v23, v45
	v_or_b32_e32 v23, v32, v22
	v_bcnt_u32_b32 v44, v23, v45
	s_cmp_lt_i32 s41, 16
	s_cbranch_scc1 .Lbs_c31
	v_and_b32_e32 v33, v25, v221
	v_bcnt_u32_b32 v42, v33, v42
	v_and_b32_e32 v22, v25, v222
	v_and_b32_e32 v23, v33, v22
	v_bcnt_u32_b32 v43, v23, v43
	v_or_b32_e32 v23, v33, v22
	v_bcnt_u32_b32 v44, v23, v44
	s_cmp_lt_i32 s41, 32
	s_cbranch_scc1 .Lbs_c31
	v_and_b32_e32 v36, v26, v249
	v_bcnt_u32_b32 v42, v36, v42
	v_and_b32_e32 v22, v26, v250
	v_and_b32_e32 v23, v36, v22
	v_bcnt_u32_b32 v43, v23, v43
	v_or_b32_e32 v23, v36, v22
	v_bcnt_u32_b32 v44, v23, v44
	s_cmp_lt_i32 s41, 48
	s_cbranch_scc1 .Lbs_c31
	v_and_b32_e32 v37, v27, v4
	v_bcnt_u32_b32 v42, v37, v42
	v_and_b32_e32 v22, v27, v5
	v_and_b32_e32 v23, v37, v22
	v_bcnt_u32_b32 v43, v23, v43
	v_or_b32_e32 v23, v37, v22
	v_bcnt_u32_b32 v44, v23, v44
.Lbs_c31:
	v_lshl_or_b32 v38, v43, 16, v42
	v_mov_b32_e32 v39, v44
	v_mov_b32_e32 v40, v38
	v_mov_b32_e32 v41, v39
	s_nop 1
	v_permlane32_swap_b32_e32 v38, v40
	v_permlane32_swap_b32_e32 v39, v41
	v_add_u32_e32 v38, v38, v40
	v_add_u32_e32 v39, v39, v41
	v_or_b32_e32 v22, v38, v39
	v_cmp_ne_u32_e32 vcc, 0, v22
	s_and_b64 vcc, vcc, s[58:59]
	s_and_saveexec_b64 s[54:55], vcc
	ds_add_u64 v48, v[38:39]
	s_mov_b64 exec, s[54:55]
	s_waitcnt lgkmcnt(0)
	s_barrier
	ds_read_b64 v[40:41], v48
	s_waitcnt lgkmcnt(0)
	v_and_b32_e32 v22, s6, v40
	v_lshrrev_b32_e32 v23, 16, v40
	v_cmp_lt_u32_e64 s[48:49], s42, v22
	v_cmp_eq_u32_e32 vcc, s43, v22
	s_andn2_b64 s[50:51], s[48:49], s[44:45]
	s_or_b64 s[48:49], s[48:49], s[44:45]
	s_andn2_b64 s[52:53], exec, s[48:49]
	s_or_b64 s[44:45], s[44:45], vcc
	v_cndmask_b32_e64 v49, v41, v23, s[50:51]
	v_cndmask_b32_e64 v46, v44, v43, s[50:51]
	v_cndmask_b32_e64 v45, v45, v42, s[52:53]
	v_cmp_lt_u32_e64 s[48:49], s42, v49
	v_cmp_eq_u32_e32 vcc, s43, v49
	s_andn2_b64 s[0:1], s[48:49], s[44:45]
	s_or_b64 s[48:49], s[48:49], s[44:45]
	s_andn2_b64 s[22:23], exec, s[48:49]
	s_or_b64 s[44:45], s[44:45], vcc
	s_or_b64 s[46:47], s[46:47], s[50:51]
	s_or_b64 s[46:47], s[46:47], s[0:1]
	v_cndmask_b32_e64 v45, v45, v46, s[22:23]
	v_cndmask_b32_e64 v46, 0, v32, s[52:53]
	v_or_b32_e32 v28, v28, v46
	v_xor_b32_e32 v46, v24, v46
	v_cndmask_b32_e64 v24, v46, v32, s[50:51]
	v_and_b32_e32 v22, v24, v173
	v_cndmask_b32_e64 v46, 0, v22, s[22:23]
	v_or_b32_e32 v28, v28, v46
	v_xor_b32_e32 v46, v24, v46
	v_cndmask_b32_e64 v24, v46, v22, s[0:1]
	s_cmp_lt_i32 s41, 16
	s_cbranch_scc1 .Lbs_u31
	v_cndmask_b32_e64 v46, 0, v33, s[52:53]
	v_or_b32_e32 v29, v29, v46
	v_xor_b32_e32 v46, v25, v46
	v_cndmask_b32_e64 v25, v46, v33, s[50:51]
	v_and_b32_e32 v22, v25, v222
	v_cndmask_b32_e64 v46, 0, v22, s[22:23]
	v_or_b32_e32 v29, v29, v46
	v_xor_b32_e32 v46, v25, v46
	v_cndmask_b32_e64 v25, v46, v22, s[0:1]
	s_cmp_lt_i32 s41, 32
	s_cbranch_scc1 .Lbs_u31
	v_cndmask_b32_e64 v46, 0, v36, s[52:53]
	v_or_b32_e32 v30, v30, v46
	v_xor_b32_e32 v46, v26, v46
	v_cndmask_b32_e64 v26, v46, v36, s[50:51]
	v_and_b32_e32 v22, v26, v250
	v_cndmask_b32_e64 v46, 0, v22, s[22:23]
	v_or_b32_e32 v30, v30, v46
	v_xor_b32_e32 v46, v26, v46
	v_cndmask_b32_e64 v26, v46, v22, s[0:1]
	s_cmp_lt_i32 s41, 48
	s_cbranch_scc1 .Lbs_u31
	v_cndmask_b32_e64 v46, 0, v37, s[52:53]
	v_or_b32_e32 v31, v31, v46
	v_xor_b32_e32 v46, v27, v46
	v_cndmask_b32_e64 v27, v46, v37, s[50:51]
	v_and_b32_e32 v22, v27, v5
	v_cndmask_b32_e64 v46, 0, v22, s[22:23]
	v_or_b32_e32 v31, v31, v46
	v_xor_b32_e32 v46, v27, v46
	v_cndmask_b32_e64 v27, v46, v22, s[0:1]
.Lbs_u31:
	s_andn2_b64 s[48:49], exec, s[44:45]
	s_cbranch_scc0 .Lbs_end
	v_and_b32_e32 v32, v24, v170
	v_bcnt_u32_b32 v42, v32, v45
	v_and_b32_e32 v22, v24, v171
	v_and_b32_e32 v23, v32, v22
	v_bcnt_u32_b32 v43, v23, v45
	v_or_b32_e32 v23, v32, v22
	v_bcnt_u32_b32 v44, v23, v45
	s_cmp_lt_i32 s41, 16
	s_cbranch_scc1 .Lbs_c29
	v_and_b32_e32 v33, v25, v219
	v_bcnt_u32_b32 v42, v33, v42
	v_and_b32_e32 v22, v25, v220
	v_and_b32_e32 v23, v33, v22
	v_bcnt_u32_b32 v43, v23, v43
	v_or_b32_e32 v23, v33, v22
	v_bcnt_u32_b32 v44, v23, v44
	s_cmp_lt_i32 s41, 32
	s_cbranch_scc1 .Lbs_c29
	v_and_b32_e32 v36, v26, v247
	v_bcnt_u32_b32 v42, v36, v42
	v_and_b32_e32 v22, v26, v248
	v_and_b32_e32 v23, v36, v22
	v_bcnt_u32_b32 v43, v23, v43
	v_or_b32_e32 v23, v36, v22
	v_bcnt_u32_b32 v44, v23, v44
	s_cmp_lt_i32 s41, 48
	s_cbranch_scc1 .Lbs_c29
	v_and_b32_e32 v37, v27, v6
	v_bcnt_u32_b32 v42, v37, v42
	v_and_b32_e32 v22, v27, v7
	v_and_b32_e32 v23, v37, v22
	v_bcnt_u32_b32 v43, v23, v43
	v_or_b32_e32 v23, v37, v22
	v_bcnt_u32_b32 v44, v23, v44
; DI void a1_task(unsigned char* shm, const bf16_t* prm, const bf16_t* prt, unsigned* mask, int b, int qt, const int tid) {
;     ...
;     unsigned T = 0u;
;     if (qt >= 8) {
;         const int nheld = (qt >= wid) ? ((qt - wid) >> 3) + 1 : 0;
;         bool done = false;
;     ...
;             const unsigned cand = T | (1u << bit);
;             int c = 0;
; #pragma unroll
;             for (int jt = 0; jt < 8; ++jt) {
;                 if (jt < nheld) {
; #pragma unroll
;                     for (int i = 0; i < 16; ++i) c += (key[jt][i] >= cand) ? 1 : 0;
;                 }
;             }
;             c += __shfl_xor(c, 32);
;             if (h == 0 && c) atomicAdd(&cnt[(31 - bit) * 32 + r], (unsigned)c);
;             __syncthreads();
;             const unsigned tot = cnt[(31 - bit) * 32 + r];
;             if (!done) { if (tot >= 256u) T = cand; if (tot == 256u) done = true; }
;             if (__ballot(!done) == 0ull) break;
;         }
;     }
.Lbs_c29:
	v_lshl_or_b32 v38, v43, 16, v42
	v_mov_b32_e32 v39, v44
	v_mov_b32_e32 v40, v38
	v_mov_b32_e32 v41, v39
	s_nop 1
	v_permlane32_swap_b32_e32 v38, v40
	v_permlane32_swap_b32_e32 v39, v41
	v_add_u32_e32 v38, v38, v40
	v_add_u32_e32 v39, v39, v41
	v_or_b32_e32 v22, v38, v39
	v_cmp_ne_u32_e32 vcc, 0, v22
	s_and_b64 vcc, vcc, s[58:59]
	s_and_saveexec_b64 s[54:55], vcc
	ds_add_u64 v48, v[38:39] offset:256
	s_mov_b64 exec, s[54:55]
	s_waitcnt lgkmcnt(0)
	s_barrier
	ds_read_b64 v[40:41], v48 offset:256
	s_waitcnt lgkmcnt(0)
	v_and_b32_e32 v22, s6, v40
	v_lshrrev_b32_e32 v23, 16, v40
	v_cmp_lt_u32_e64 s[48:49], s42, v22
	v_cmp_eq_u32_e32 vcc, s43, v22
	s_andn2_b64 s[50:51], s[48:49], s[44:45]
	s_or_b64 s[48:49], s[48:49], s[44:45]
	s_andn2_b64 s[52:53], exec, s[48:49]
	s_or_b64 s[44:45], s[44:45], vcc
	v_cndmask_b32_e64 v49, v41, v23, s[50:51]
	v_cndmask_b32_e64 v46, v44, v43, s[50:51]
	v_cndmask_b32_e64 v45, v45, v42, s[52:53]
	v_cmp_lt_u32_e64 s[48:49], s42, v49
	v_cmp_eq_u32_e32 vcc, s43, v49
	s_andn2_b64 s[0:1], s[48:49], s[44:45]
	s_or_b64 s[48:49], s[48:49], s[44:45]
	s_andn2_b64 s[22:23], exec, s[48:49]
	s_or_b64 s[44:45], s[44:45], vcc
	s_or_b64 s[46:47], s[46:47], s[50:51]
	s_or_b64 s[46:47], s[46:47], s[0:1]
	v_cndmask_b32_e64 v45, v45, v46, s[22:23]
	v_cndmask_b32_e64 v46, 0, v32, s[52:53]
	v_or_b32_e32 v28, v28, v46
	v_xor_b32_e32 v46, v24, v46
	v_cndmask_b32_e64 v24, v46, v32, s[50:51]
	v_and_b32_e32 v22, v24, v171
	v_cndmask_b32_e64 v46, 0, v22, s[22:23]
	v_or_b32_e32 v28, v28, v46
	v_xor_b32_e32 v46, v24, v46
	v_cndmask_b32_e64 v24, v46, v22, s[0:1]
	s_cmp_lt_i32 s41, 16
	s_cbranch_scc1 .Lbs_u29
	v_cndmask_b32_e64 v46, 0, v33, s[52:53]
	v_or_b32_e32 v29, v29, v46
	v_xor_b32_e32 v46, v25, v46
	v_cndmask_b32_e64 v25, v46, v33, s[50:51]
	v_and_b32_e32 v22, v25, v220
	v_cndmask_b32_e64 v46, 0, v22, s[22:23]
	v_or_b32_e32 v29, v29, v46
	v_xor_b32_e32 v46, v25, v46
	v_cndmask_b32_e64 v25, v46, v22, s[0:1]
	s_cmp_lt_i32 s41, 32
	s_cbranch_scc1 .Lbs_u29
	v_cndmask_b32_e64 v46, 0, v36, s[52:53]
	v_or_b32_e32 v30, v30, v46
	v_xor_b32_e32 v46, v26, v46
	v_cndmask_b32_e64 v26, v46, v36, s[50:51]
	v_and_b32_e32 v22, v26, v248
	v_cndmask_b32_e64 v46, 0, v22, s[22:23]
	v_or_b32_e32 v30, v30, v46
	v_xor_b32_e32 v46, v26, v46
	v_cndmask_b32_e64 v26, v46, v22, s[0:1]
	s_cmp_lt_i32 s41, 48
	s_cbranch_scc1 .Lbs_u29
	v_cndmask_b32_e64 v46, 0, v37, s[52:53]
	v_or_b32_e32 v31, v31, v46
	v_xor_b32_e32 v46, v27, v46
	v_cndmask_b32_e64 v27, v46, v37, s[50:51]
	v_and_b32_e32 v22, v27, v7
	v_cndmask_b32_e64 v46, 0, v22, s[22:23]
	v_or_b32_e32 v31, v31, v46
	v_xor_b32_e32 v46, v27, v46
	v_cndmask_b32_e64 v27, v46, v22, s[0:1]
.Lbs_u29:
	s_andn2_b64 s[48:49], exec, s[44:45]
	s_cbranch_scc0 .Lbs_end
	v_and_b32_e32 v32, v24, v168
	v_bcnt_u32_b32 v42, v32, v45
	v_and_b32_e32 v22, v24, v169
	v_and_b32_e32 v23, v32, v22
	v_bcnt_u32_b32 v43, v23, v45
	v_or_b32_e32 v23, v32, v22
	v_bcnt_u32_b32 v44, v23, v45
	s_cmp_lt_i32 s41, 16
	s_cbranch_scc1 .Lbs_c27
	v_and_b32_e32 v33, v25, v217
	v_bcnt_u32_b32 v42, v33, v42
	v_and_b32_e32 v22, v25, v218
	v_and_b32_e32 v23, v33, v22
	v_bcnt_u32_b32 v43, v23, v43
	v_or_b32_e32 v23, v33, v22
	v_bcnt_u32_b32 v44, v23, v44
	s_cmp_lt_i32 s41, 32
	s_cbranch_scc1 .Lbs_c27
	v_and_b32_e32 v36, v26, v245
	v_bcnt_u32_b32 v42, v36, v42
	v_and_b32_e32 v22, v26, v246
	v_and_b32_e32 v23, v36, v22
	v_bcnt_u32_b32 v43, v23, v43
	v_or_b32_e32 v23, v36, v22
	v_bcnt_u32_b32 v44, v23, v44
	s_cmp_lt_i32 s41, 48
	s_cbranch_scc1 .Lbs_c27
	v_and_b32_e32 v37, v27, v8
	v_bcnt_u32_b32 v42, v37, v42
	v_and_b32_e32 v22, v27, v9
	v_and_b32_e32 v23, v37, v22
	v_bcnt_u32_b32 v43, v23, v43
	v_or_b32_e32 v23, v37, v22
	v_bcnt_u32_b32 v44, v23, v44
.Lbs_c27:
	v_lshl_or_b32 v38, v43, 16, v42
	v_mov_b32_e32 v39, v44
	v_mov_b32_e32 v40, v38
	v_mov_b32_e32 v41, v39
	s_nop 1
	v_permlane32_swap_b32_e32 v38, v40
	v_permlane32_swap_b32_e32 v39, v41
	v_add_u32_e32 v38, v38, v40
	v_add_u32_e32 v39, v39, v41
	v_or_b32_e32 v22, v38, v39
	v_cmp_ne_u32_e32 vcc, 0, v22
	s_and_b64 vcc, vcc, s[58:59]
	s_and_saveexec_b64 s[54:55], vcc
	ds_add_u64 v48, v[38:39] offset:512
	s_mov_b64 exec, s[54:55]
	s_waitcnt lgkmcnt(0)
	s_barrier
	ds_read_b64 v[40:41], v48 offset:512
	s_waitcnt lgkmcnt(0)
	v_and_b32_e32 v22, s6, v40
	v_lshrrev_b32_e32 v23, 16, v40
	v_cmp_lt_u32_e64 s[48:49], s42, v22
	v_cmp_eq_u32_e32 vcc, s43, v22
	s_andn2_b64 s[50:51], s[48:49], s[44:45]
	s_or_b64 s[48:49], s[48:49], s[44:45]
	s_andn2_b64 s[52:53], exec, s[48:49]
	s_or_b64 s[44:45], s[44:45], vcc
	v_cndmask_b32_e64 v49, v41, v23, s[50:51]
	v_cndmask_b32_e64 v46, v44, v43, s[50:51]
	v_cndmask_b32_e64 v45, v45, v42, s[52:53]
	v_cmp_lt_u32_e64 s[48:49], s42, v49
	v_cmp_eq_u32_e32 vcc, s43, v49
	s_andn2_b64 s[0:1], s[48:49], s[44:45]
	s_or_b64 s[48:49], s[48:49], s[44:45]
	s_andn2_b64 s[22:23], exec, s[48:49]
	s_or_b64 s[44:45], s[44:45], vcc
	s_or_b64 s[46:47], s[46:47], s[50:51]
	s_or_b64 s[46:47], s[46:47], s[0:1]
	v_cndmask_b32_e64 v45, v45, v46, s[22:23]
	v_cndmask_b32_e64 v46, 0, v32, s[52:53]
	v_or_b32_e32 v28, v28, v46
	v_xor_b32_e32 v46, v24, v46
	v_cndmask_b32_e64 v24, v46, v32, s[50:51]
	v_and_b32_e32 v22, v24, v169
	v_cndmask_b32_e64 v46, 0, v22, s[22:23]
	v_or_b32_e32 v28, v28, v46
	v_xor_b32_e32 v46, v24, v46
	v_cndmask_b32_e64 v24, v46, v22, s[0:1]
	s_cmp_lt_i32 s41, 16
	s_cbranch_scc1 .Lbs_u27
	v_cndmask_b32_e64 v46, 0, v33, s[52:53]
	v_or_b32_e32 v29, v29, v46
	v_xor_b32_e32 v46, v25, v46
	v_cndmask_b32_e64 v25, v46, v33, s[50:51]
	v_and_b32_e32 v22, v25, v218
	v_cndmask_b32_e64 v46, 0, v22, s[22:23]
	v_or_b32_e32 v29, v29, v46
	v_xor_b32_e32 v46, v25, v46
	v_cndmask_b32_e64 v25, v46, v22, s[0:1]
	s_cmp_lt_i32 s41, 32
	s_cbranch_scc1 .Lbs_u27
	v_cndmask_b32_e64 v46, 0, v36, s[52:53]
	v_or_b32_e32 v30, v30, v46
	v_xor_b32_e32 v46, v26, v46
	v_cndmask_b32_e64 v26, v46, v36, s[50:51]
	v_and_b32_e32 v22, v26, v246
	v_cndmask_b32_e64 v46, 0, v22, s[22:23]
	v_or_b32_e32 v30, v30, v46
	v_xor_b32_e32 v46, v26, v46
	v_cndmask_b32_e64 v26, v46, v22, s[0:1]
	s_cmp_lt_i32 s41, 48
	s_cbranch_scc1 .Lbs_u27
	v_cndmask_b32_e64 v46, 0, v37, s[52:53]
	v_or_b32_e32 v31, v31, v46
	v_xor_b32_e32 v46, v27, v46
	v_cndmask_b32_e64 v27, v46, v37, s[50:51]
	v_and_b32_e32 v22, v27, v9
	v_cndmask_b32_e64 v46, 0, v22, s[22:23]
	v_or_b32_e32 v31, v31, v46
	v_xor_b32_e32 v46, v27, v46
	v_cndmask_b32_e64 v27, v46, v22, s[0:1]
; DI void a1_task(unsigned char* shm, const bf16_t* prm, const bf16_t* prt, unsigned* mask, int b, int qt, const int tid) {
;     ...
;     unsigned T = 0u;
;     if (qt >= 8) {
;         const int nheld = (qt >= wid) ? ((qt - wid) >> 3) + 1 : 0;
;         bool done = false;
;     ...
;             const unsigned cand = T | (1u << bit);
;             int c = 0;
; #pragma unroll
;             for (int jt = 0; jt < 8; ++jt) {
;                 if (jt < nheld) {
; #pragma unroll
;                     for (int i = 0; i < 16; ++i) c += (key[jt][i] >= cand) ? 1 : 0;
;                 }
;             }
;             c += __shfl_xor(c, 32);
;             if (h == 0 && c) atomicAdd(&cnt[(31 - bit) * 32 + r], (unsigned)c);
;             __syncthreads();
;             const unsigned tot = cnt[(31 - bit) * 32 + r];
;             if (!done) { if (tot >= 256u) T = cand; if (tot == 256u) done = true; }
;             if (__ballot(!done) == 0ull) break;
;         }
;     }
.Lbs_u27:
	s_andn2_b64 s[48:49], exec, s[44:45]
	s_cbranch_scc0 .Lbs_end
	v_and_b32_e32 v32, v24, v164
	v_bcnt_u32_b32 v42, v32, v45
	v_and_b32_e32 v22, v24, v165
	v_and_b32_e32 v23, v32, v22
	v_bcnt_u32_b32 v43, v23, v45
	v_or_b32_e32 v23, v32, v22
	v_bcnt_u32_b32 v44, v23, v45
	s_cmp_lt_i32 s41, 16
	s_cbranch_scc1 .Lbs_c25
	v_and_b32_e32 v33, v25, v215
	v_bcnt_u32_b32 v42, v33, v42
	v_and_b32_e32 v22, v25, v216
	v_and_b32_e32 v23, v33, v22
	v_bcnt_u32_b32 v43, v23, v43
	v_or_b32_e32 v23, v33, v22
	v_bcnt_u32_b32 v44, v23, v44
	s_cmp_lt_i32 s41, 32
	s_cbranch_scc1 .Lbs_c25
	v_and_b32_e32 v36, v26, v231
	v_bcnt_u32_b32 v42, v36, v42
	v_and_b32_e32 v22, v26, v244
	v_and_b32_e32 v23, v36, v22
	v_bcnt_u32_b32 v43, v23, v43
	v_or_b32_e32 v23, v36, v22
	v_bcnt_u32_b32 v44, v23, v44
	s_cmp_lt_i32 s41, 48
	s_cbranch_scc1 .Lbs_c25
	v_and_b32_e32 v37, v27, v10
	v_bcnt_u32_b32 v42, v37, v42
	v_and_b32_e32 v22, v27, v11
	v_and_b32_e32 v23, v37, v22
	v_bcnt_u32_b32 v43, v23, v43
	v_or_b32_e32 v23, v37, v22
	v_bcnt_u32_b32 v44, v23, v44
.Lbs_c25:
	v_lshl_or_b32 v38, v43, 16, v42
	v_mov_b32_e32 v39, v44
	v_mov_b32_e32 v40, v38
	v_mov_b32_e32 v41, v39
	s_nop 1
	v_permlane32_swap_b32_e32 v38, v40
	v_permlane32_swap_b32_e32 v39, v41
	v_add_u32_e32 v38, v38, v40
	v_add_u32_e32 v39, v39, v41
	v_or_b32_e32 v22, v38, v39
	v_cmp_ne_u32_e32 vcc, 0, v22
	s_and_b64 vcc, vcc, s[58:59]
	s_and_saveexec_b64 s[54:55], vcc
	ds_add_u64 v48, v[38:39] offset:768
	s_mov_b64 exec, s[54:55]
	s_waitcnt lgkmcnt(0)
	s_barrier
	ds_read_b64 v[40:41], v48 offset:768
	s_waitcnt lgkmcnt(0)
	v_and_b32_e32 v22, s6, v40
	v_lshrrev_b32_e32 v23, 16, v40
	v_cmp_lt_u32_e64 s[48:49], s42, v22
	v_cmp_eq_u32_e32 vcc, s43, v22
	s_andn2_b64 s[50:51], s[48:49], s[44:45]
	s_or_b64 s[48:49], s[48:49], s[44:45]
	s_andn2_b64 s[52:53], exec, s[48:49]
	s_or_b64 s[44:45], s[44:45], vcc
	v_cndmask_b32_e64 v49, v41, v23, s[50:51]
	v_cndmask_b32_e64 v46, v44, v43, s[50:51]
	v_cndmask_b32_e64 v45, v45, v42, s[52:53]
	v_cmp_lt_u32_e64 s[48:49], s42, v49
	v_cmp_eq_u32_e32 vcc, s43, v49
	s_andn2_b64 s[0:1], s[48:49], s[44:45]
	s_or_b64 s[48:49], s[48:49], s[44:45]
	s_andn2_b64 s[22:23], exec, s[48:49]
	s_or_b64 s[44:45], s[44:45], vcc
	s_or_b64 s[46:47], s[46:47], s[50:51]
	s_or_b64 s[46:47], s[46:47], s[0:1]
	v_cndmask_b32_e64 v45, v45, v46, s[22:23]
	v_cndmask_b32_e64 v46, 0, v32, s[52:53]
	v_or_b32_e32 v28, v28, v46
	v_xor_b32_e32 v46, v24, v46
	v_cndmask_b32_e64 v24, v46, v32, s[50:51]
	v_and_b32_e32 v22, v24, v165
	v_cndmask_b32_e64 v46, 0, v22, s[22:23]
	v_or_b32_e32 v28, v28, v46
	v_xor_b32_e32 v46, v24, v46
	v_cndmask_b32_e64 v24, v46, v22, s[0:1]
	s_cmp_lt_i32 s41, 16
	s_cbranch_scc1 .Lbs_u25
	v_cndmask_b32_e64 v46, 0, v33, s[52:53]
	v_or_b32_e32 v29, v29, v46
	v_xor_b32_e32 v46, v25, v46
	v_cndmask_b32_e64 v25, v46, v33, s[50:51]
	v_and_b32_e32 v22, v25, v216
	v_cndmask_b32_e64 v46, 0, v22, s[22:23]
	v_or_b32_e32 v29, v29, v46
	v_xor_b32_e32 v46, v25, v46
	v_cndmask_b32_e64 v25, v46, v22, s[0:1]
	s_cmp_lt_i32 s41, 32
	s_cbranch_scc1 .Lbs_u25
	v_cndmask_b32_e64 v46, 0, v36, s[52:53]
	v_or_b32_e32 v30, v30, v46
	v_xor_b32_e32 v46, v26, v46
	v_cndmask_b32_e64 v26, v46, v36, s[50:51]
	v_and_b32_e32 v22, v26, v244
	v_cndmask_b32_e64 v46, 0, v22, s[22:23]
	v_or_b32_e32 v30, v30, v46
	v_xor_b32_e32 v46, v26, v46
	v_cndmask_b32_e64 v26, v46, v22, s[0:1]
	s_cmp_lt_i32 s41, 48
	s_cbranch_scc1 .Lbs_u25
	v_cndmask_b32_e64 v46, 0, v37, s[52:53]
	v_or_b32_e32 v31, v31, v46
	v_xor_b32_e32 v46, v27, v46
	v_cndmask_b32_e64 v27, v46, v37, s[50:51]
	v_and_b32_e32 v22, v27, v11
	v_cndmask_b32_e64 v46, 0, v22, s[22:23]
	v_or_b32_e32 v31, v31, v46
	v_xor_b32_e32 v46, v27, v46
	v_cndmask_b32_e64 v27, v46, v22, s[0:1]
.Lbs_u25:
	s_andn2_b64 s[48:49], exec, s[44:45]
	s_cbranch_scc0 .Lbs_end
	v_and_b32_e32 v32, v24, v163
	v_bcnt_u32_b32 v42, v32, v45
	v_and_b32_e32 v22, v24, v160
	v_and_b32_e32 v23, v32, v22
	v_bcnt_u32_b32 v43, v23, v45
	v_or_b32_e32 v23, v32, v22
	v_bcnt_u32_b32 v44, v23, v45
	s_cmp_lt_i32 s41, 16
	s_cbranch_scc1 .Lbs_c23
	v_and_b32_e32 v33, v25, v214
	v_bcnt_u32_b32 v42, v33, v42
	v_and_b32_e32 v22, v25, v211
	v_and_b32_e32 v23, v33, v22
	v_bcnt_u32_b32 v43, v23, v43
	v_or_b32_e32 v23, v33, v22
	v_bcnt_u32_b32 v44, v23, v44
	s_cmp_lt_i32 s41, 32
	s_cbranch_scc1 .Lbs_c23
	v_and_b32_e32 v36, v26, v97
	v_bcnt_u32_b32 v42, v36, v42
	v_and_b32_e32 v22, v26, v94
	v_and_b32_e32 v23, v36, v22
	v_bcnt_u32_b32 v43, v23, v43
	v_or_b32_e32 v23, v36, v22
	v_bcnt_u32_b32 v44, v23, v44
	s_cmp_lt_i32 s41, 48
	s_cbranch_scc1 .Lbs_c23
	v_and_b32_e32 v37, v27, v13
	v_bcnt_u32_b32 v42, v37, v42
	v_and_b32_e32 v22, v27, v14
	v_and_b32_e32 v23, v37, v22
	v_bcnt_u32_b32 v43, v23, v43
	v_or_b32_e32 v23, v37, v22
	v_bcnt_u32_b32 v44, v23, v44
; DI void a1_task(unsigned char* shm, const bf16_t* prm, const bf16_t* prt, unsigned* mask, int b, int qt, const int tid) {
;     ...
;     unsigned T = 0u;
;     if (qt >= 8) {
;         const int nheld = (qt >= wid) ? ((qt - wid) >> 3) + 1 : 0;
;         bool done = false;
;     ...
;             const unsigned cand = T | (1u << bit);
;             int c = 0;
; #pragma unroll
;             for (int jt = 0; jt < 8; ++jt) {
;                 if (jt < nheld) {
; #pragma unroll
;                     for (int i = 0; i < 16; ++i) c += (key[jt][i] >= cand) ? 1 : 0;
;                 }
;             }
;             c += __shfl_xor(c, 32);
;             if (h == 0 && c) atomicAdd(&cnt[(31 - bit) * 32 + r], (unsigned)c);
;             __syncthreads();
;             const unsigned tot = cnt[(31 - bit) * 32 + r];
;             if (!done) { if (tot >= 256u) T = cand; if (tot == 256u) done = true; }
;             if (__ballot(!done) == 0ull) break;
;         }
;     }
.Lbs_c23:
	v_lshl_or_b32 v38, v43, 16, v42
	v_mov_b32_e32 v39, v44
	v_mov_b32_e32 v40, v38
	v_mov_b32_e32 v41, v39
	s_nop 1
	v_permlane32_swap_b32_e32 v38, v40
	v_permlane32_swap_b32_e32 v39, v41
	v_add_u32_e32 v38, v38, v40
	v_add_u32_e32 v39, v39, v41
	v_or_b32_e32 v22, v38, v39
	v_cmp_ne_u32_e32 vcc, 0, v22
	s_and_b64 vcc, vcc, s[58:59]
	s_and_saveexec_b64 s[54:55], vcc
	ds_add_u64 v48, v[38:39] offset:1024
	s_mov_b64 exec, s[54:55]
	s_waitcnt lgkmcnt(0)
	s_barrier
	ds_read_b64 v[40:41], v48 offset:1024
	s_waitcnt lgkmcnt(0)
	v_and_b32_e32 v22, s6, v40
	v_lshrrev_b32_e32 v23, 16, v40
	v_cmp_lt_u32_e64 s[48:49], s42, v22
	v_cmp_eq_u32_e32 vcc, s43, v22
	s_andn2_b64 s[50:51], s[48:49], s[44:45]
	s_or_b64 s[48:49], s[48:49], s[44:45]
	s_andn2_b64 s[52:53], exec, s[48:49]
	s_or_b64 s[44:45], s[44:45], vcc
	v_cndmask_b32_e64 v49, v41, v23, s[50:51]
	v_cndmask_b32_e64 v46, v44, v43, s[50:51]
	v_cndmask_b32_e64 v45, v45, v42, s[52:53]
	v_cmp_lt_u32_e64 s[48:49], s42, v49
	v_cmp_eq_u32_e32 vcc, s43, v49
	s_andn2_b64 s[0:1], s[48:49], s[44:45]
	s_or_b64 s[48:49], s[48:49], s[44:45]
	s_andn2_b64 s[22:23], exec, s[48:49]
	s_or_b64 s[44:45], s[44:45], vcc
	s_or_b64 s[46:47], s[46:47], s[50:51]
	s_or_b64 s[46:47], s[46:47], s[0:1]
	v_cndmask_b32_e64 v45, v45, v46, s[22:23]
	v_cndmask_b32_e64 v46, 0, v32, s[52:53]
	v_or_b32_e32 v28, v28, v46
	v_xor_b32_e32 v46, v24, v46
	v_cndmask_b32_e64 v24, v46, v32, s[50:51]
	v_and_b32_e32 v22, v24, v160
	v_cndmask_b32_e64 v46, 0, v22, s[22:23]
	v_or_b32_e32 v28, v28, v46
	v_xor_b32_e32 v46, v24, v46
	v_cndmask_b32_e64 v24, v46, v22, s[0:1]
	s_cmp_lt_i32 s41, 16
	s_cbranch_scc1 .Lbs_u23
	v_cndmask_b32_e64 v46, 0, v33, s[52:53]
	v_or_b32_e32 v29, v29, v46
	v_xor_b32_e32 v46, v25, v46
	v_cndmask_b32_e64 v25, v46, v33, s[50:51]
	v_and_b32_e32 v22, v25, v211
	v_cndmask_b32_e64 v46, 0, v22, s[22:23]
	v_or_b32_e32 v29, v29, v46
	v_xor_b32_e32 v46, v25, v46
	v_cndmask_b32_e64 v25, v46, v22, s[0:1]
	s_cmp_lt_i32 s41, 32
	s_cbranch_scc1 .Lbs_u23
	v_cndmask_b32_e64 v46, 0, v36, s[52:53]
	v_or_b32_e32 v30, v30, v46
	v_xor_b32_e32 v46, v26, v46
	v_cndmask_b32_e64 v26, v46, v36, s[50:51]
	v_and_b32_e32 v22, v26, v94
	v_cndmask_b32_e64 v46, 0, v22, s[22:23]
	v_or_b32_e32 v30, v30, v46
	v_xor_b32_e32 v46, v26, v46
	v_cndmask_b32_e64 v26, v46, v22, s[0:1]
	s_cmp_lt_i32 s41, 48
	s_cbranch_scc1 .Lbs_u23
	v_cndmask_b32_e64 v46, 0, v37, s[52:53]
	v_or_b32_e32 v31, v31, v46
	v_xor_b32_e32 v46, v27, v46
	v_cndmask_b32_e64 v27, v46, v37, s[50:51]
	v_and_b32_e32 v22, v27, v14
	v_cndmask_b32_e64 v46, 0, v22, s[22:23]
	v_or_b32_e32 v31, v31, v46
	v_xor_b32_e32 v46, v27, v46
	v_cndmask_b32_e64 v27, v46, v22, s[0:1]
.Lbs_u23:
	s_andn2_b64 s[48:49], exec, s[44:45]
	s_cbranch_scc0 .Lbs_end
	v_and_b32_e32 v32, v24, v161
	v_bcnt_u32_b32 v42, v32, v45
	v_and_b32_e32 v22, v24, v158
	v_and_b32_e32 v23, v32, v22
	v_bcnt_u32_b32 v43, v23, v45
	v_or_b32_e32 v23, v32, v22
	v_bcnt_u32_b32 v44, v23, v45
	s_cmp_lt_i32 s41, 16
	s_cbranch_scc1 .Lbs_c21
	v_and_b32_e32 v33, v25, v212
	v_bcnt_u32_b32 v42, v33, v42
	v_and_b32_e32 v22, v25, v192
	v_and_b32_e32 v23, v33, v22
	v_bcnt_u32_b32 v43, v23, v43
	v_or_b32_e32 v23, v33, v22
	v_bcnt_u32_b32 v44, v23, v44
	s_cmp_lt_i32 s41, 32
	s_cbranch_scc1 .Lbs_c21
	v_and_b32_e32 v36, v26, v95
	v_bcnt_u32_b32 v42, v36, v42
	v_and_b32_e32 v22, v26, v88
	v_and_b32_e32 v23, v36, v22
	v_bcnt_u32_b32 v43, v23, v43
	v_or_b32_e32 v23, v36, v22
	v_bcnt_u32_b32 v44, v23, v44
	s_cmp_lt_i32 s41, 48
	s_cbranch_scc1 .Lbs_c21
	v_and_b32_e32 v37, v27, v15
	v_bcnt_u32_b32 v42, v37, v42
	v_and_b32_e32 v22, v27, v16
	v_and_b32_e32 v23, v37, v22
	v_bcnt_u32_b32 v43, v23, v43
	v_or_b32_e32 v23, v37, v22
	v_bcnt_u32_b32 v44, v23, v44
.Lbs_c21:
	v_lshl_or_b32 v38, v43, 16, v42
	v_mov_b32_e32 v39, v44
	v_mov_b32_e32 v40, v38
	v_mov_b32_e32 v41, v39
	s_nop 1
	v_permlane32_swap_b32_e32 v38, v40
	v_permlane32_swap_b32_e32 v39, v41
	v_add_u32_e32 v38, v38, v40
	v_add_u32_e32 v39, v39, v41
	v_or_b32_e32 v22, v38, v39
	v_cmp_ne_u32_e32 vcc, 0, v22
	s_and_b64 vcc, vcc, s[58:59]
	s_and_saveexec_b64 s[54:55], vcc
	ds_add_u64 v48, v[38:39] offset:1280
	s_mov_b64 exec, s[54:55]
	s_waitcnt lgkmcnt(0)
	s_barrier
	ds_read_b64 v[40:41], v48 offset:1280
	s_waitcnt lgkmcnt(0)
	v_and_b32_e32 v22, s6, v40
	v_lshrrev_b32_e32 v23, 16, v40
	v_cmp_lt_u32_e64 s[48:49], s42, v22
	v_cmp_eq_u32_e32 vcc, s43, v22
	s_andn2_b64 s[50:51], s[48:49], s[44:45]
	s_or_b64 s[48:49], s[48:49], s[44:45]
	s_andn2_b64 s[52:53], exec, s[48:49]
	s_or_b64 s[44:45], s[44:45], vcc
	v_cndmask_b32_e64 v49, v41, v23, s[50:51]
	v_cndmask_b32_e64 v46, v44, v43, s[50:51]
	v_cndmask_b32_e64 v45, v45, v42, s[52:53]
	v_cmp_lt_u32_e64 s[48:49], s42, v49
	v_cmp_eq_u32_e32 vcc, s43, v49
	s_andn2_b64 s[0:1], s[48:49], s[44:45]
	s_or_b64 s[48:49], s[48:49], s[44:45]
	s_andn2_b64 s[22:23], exec, s[48:49]
	s_or_b64 s[44:45], s[44:45], vcc
	s_or_b64 s[46:47], s[46:47], s[50:51]
	s_or_b64 s[46:47], s[46:47], s[0:1]
	v_cndmask_b32_e64 v45, v45, v46, s[22:23]
	v_cndmask_b32_e64 v46, 0, v32, s[52:53]
	v_or_b32_e32 v28, v28, v46
	v_xor_b32_e32 v46, v24, v46
	v_cndmask_b32_e64 v24, v46, v32, s[50:51]
	v_and_b32_e32 v22, v24, v158
	v_cndmask_b32_e64 v46, 0, v22, s[22:23]
	v_or_b32_e32 v28, v28, v46
	v_xor_b32_e32 v46, v24, v46
	v_cndmask_b32_e64 v24, v46, v22, s[0:1]
	s_cmp_lt_i32 s41, 16
	s_cbranch_scc1 .Lbs_u21
	v_cndmask_b32_e64 v46, 0, v33, s[52:53]
	v_or_b32_e32 v29, v29, v46
	v_xor_b32_e32 v46, v25, v46
	v_cndmask_b32_e64 v25, v46, v33, s[50:51]
	v_and_b32_e32 v22, v25, v192
	v_cndmask_b32_e64 v46, 0, v22, s[22:23]
	v_or_b32_e32 v29, v29, v46
	v_xor_b32_e32 v46, v25, v46
	v_cndmask_b32_e64 v25, v46, v22, s[0:1]
	s_cmp_lt_i32 s41, 32
	s_cbranch_scc1 .Lbs_u21
	v_cndmask_b32_e64 v46, 0, v36, s[52:53]
	v_or_b32_e32 v30, v30, v46
	v_xor_b32_e32 v46, v26, v46
	v_cndmask_b32_e64 v26, v46, v36, s[50:51]
	v_and_b32_e32 v22, v26, v88
	v_cndmask_b32_e64 v46, 0, v22, s[22:23]
	v_or_b32_e32 v30, v30, v46
	v_xor_b32_e32 v46, v26, v46
	v_cndmask_b32_e64 v26, v46, v22, s[0:1]
	s_cmp_lt_i32 s41, 48
	s_cbranch_scc1 .Lbs_u21
	v_cndmask_b32_e64 v46, 0, v37, s[52:53]
	v_or_b32_e32 v31, v31, v46
	v_xor_b32_e32 v46, v27, v46
	v_cndmask_b32_e64 v27, v46, v37, s[50:51]
	v_and_b32_e32 v22, v27, v16
	v_cndmask_b32_e64 v46, 0, v22, s[22:23]
	v_or_b32_e32 v31, v31, v46
	v_xor_b32_e32 v46, v27, v46
	v_cndmask_b32_e64 v27, v46, v22, s[0:1]
; DI void a1_task(unsigned char* shm, const bf16_t* prm, const bf16_t* prt, unsigned* mask, int b, int qt, const int tid) {
;     ...
;     unsigned T = 0u;
;     if (qt >= 8) {
;         const int nheld = (qt >= wid) ? ((qt - wid) >> 3) + 1 : 0;
;         bool done = false;
;     ...
;             const unsigned cand = T | (1u << bit);
;             int c = 0;
; #pragma unroll
;             for (int jt = 0; jt < 8; ++jt) {
;                 if (jt < nheld) {
; #pragma unroll
;                     for (int i = 0; i < 16; ++i) c += (key[jt][i] >= cand) ? 1 : 0;
;                 }
;             }
;             c += __shfl_xor(c, 32);
;             if (h == 0 && c) atomicAdd(&cnt[(31 - bit) * 32 + r], (unsigned)c);
;             __syncthreads();
;             const unsigned tot = cnt[(31 - bit) * 32 + r];
;             if (!done) { if (tot >= 256u) T = cand; if (tot == 256u) done = true; }
;             if (__ballot(!done) == 0ull) break;
;         }
;     }
.Lbs_u21:
	s_andn2_b64 s[48:49], exec, s[44:45]
	s_cbranch_scc0 .Lbs_end
	v_and_b32_e32 v32, v24, v159
	v_bcnt_u32_b32 v42, v32, v45
	v_and_b32_e32 v22, v24, v167
	v_and_b32_e32 v23, v32, v22
	v_bcnt_u32_b32 v43, v23, v45
	v_or_b32_e32 v23, v32, v22
	v_bcnt_u32_b32 v44, v23, v45
	s_cmp_lt_i32 s41, 16
	s_cbranch_scc1 .Lbs_c19
	v_and_b32_e32 v33, v25, v193
	v_bcnt_u32_b32 v42, v33, v42
	v_and_b32_e32 v22, v25, v190
	v_and_b32_e32 v23, v33, v22
	v_bcnt_u32_b32 v43, v23, v43
	v_or_b32_e32 v23, v33, v22
	v_bcnt_u32_b32 v44, v23, v44
	s_cmp_lt_i32 s41, 32
	s_cbranch_scc1 .Lbs_c19
	v_and_b32_e32 v36, v26, v89
	v_bcnt_u32_b32 v42, v36, v42
	v_and_b32_e32 v22, v26, v86
	v_and_b32_e32 v23, v36, v22
	v_bcnt_u32_b32 v43, v23, v43
	v_or_b32_e32 v23, v36, v22
	v_bcnt_u32_b32 v44, v23, v44
	s_cmp_lt_i32 s41, 48
	s_cbranch_scc1 .Lbs_c19
	v_and_b32_e32 v37, v27, v17
	v_bcnt_u32_b32 v42, v37, v42
	v_and_b32_e32 v22, v27, v34
	v_and_b32_e32 v23, v37, v22
	v_bcnt_u32_b32 v43, v23, v43
	v_or_b32_e32 v23, v37, v22
	v_bcnt_u32_b32 v44, v23, v44
.Lbs_c19:
	v_lshl_or_b32 v38, v43, 16, v42
	v_mov_b32_e32 v39, v44
	v_mov_b32_e32 v40, v38
	v_mov_b32_e32 v41, v39
	s_nop 1
	v_permlane32_swap_b32_e32 v38, v40
	v_permlane32_swap_b32_e32 v39, v41
	v_add_u32_e32 v38, v38, v40
	v_add_u32_e32 v39, v39, v41
	v_or_b32_e32 v22, v38, v39
	v_cmp_ne_u32_e32 vcc, 0, v22
	s_and_b64 vcc, vcc, s[58:59]
	s_and_saveexec_b64 s[54:55], vcc
	ds_add_u64 v48, v[38:39] offset:1536
	s_mov_b64 exec, s[54:55]
	s_waitcnt lgkmcnt(0)
	s_barrier
	ds_read_b64 v[40:41], v48 offset:1536
	s_waitcnt lgkmcnt(0)
	v_and_b32_e32 v22, s6, v40
	v_lshrrev_b32_e32 v23, 16, v40
	v_cmp_lt_u32_e64 s[48:49], s42, v22
	v_cmp_eq_u32_e32 vcc, s43, v22
	s_andn2_b64 s[50:51], s[48:49], s[44:45]
	s_or_b64 s[48:49], s[48:49], s[44:45]
	s_andn2_b64 s[52:53], exec, s[48:49]
	s_or_b64 s[44:45], s[44:45], vcc
	v_cndmask_b32_e64 v49, v41, v23, s[50:51]
	v_cndmask_b32_e64 v46, v44, v43, s[50:51]
	v_cndmask_b32_e64 v45, v45, v42, s[52:53]
	v_cmp_lt_u32_e64 s[48:49], s42, v49
	v_cmp_eq_u32_e32 vcc, s43, v49
	s_andn2_b64 s[0:1], s[48:49], s[44:45]
	s_or_b64 s[48:49], s[48:49], s[44:45]
	s_andn2_b64 s[22:23], exec, s[48:49]
	s_or_b64 s[44:45], s[44:45], vcc
	s_or_b64 s[46:47], s[46:47], s[50:51]
	s_or_b64 s[46:47], s[46:47], s[0:1]
	v_cndmask_b32_e64 v45, v45, v46, s[22:23]
	v_cndmask_b32_e64 v46, 0, v32, s[52:53]
	v_or_b32_e32 v28, v28, v46
	v_xor_b32_e32 v46, v24, v46
	v_cndmask_b32_e64 v24, v46, v32, s[50:51]
	v_and_b32_e32 v22, v24, v167
	v_cndmask_b32_e64 v46, 0, v22, s[22:23]
	v_or_b32_e32 v28, v28, v46
	v_xor_b32_e32 v46, v24, v46
	v_cndmask_b32_e64 v24, v46, v22, s[0:1]
	s_cmp_lt_i32 s41, 16
	s_cbranch_scc1 .Lbs_u19
	v_cndmask_b32_e64 v46, 0, v33, s[52:53]
	v_or_b32_e32 v29, v29, v46
	v_xor_b32_e32 v46, v25, v46
	v_cndmask_b32_e64 v25, v46, v33, s[50:51]
	v_and_b32_e32 v22, v25, v190
	v_cndmask_b32_e64 v46, 0, v22, s[22:23]
	v_or_b32_e32 v29, v29, v46
	v_xor_b32_e32 v46, v25, v46
	v_cndmask_b32_e64 v25, v46, v22, s[0:1]
	s_cmp_lt_i32 s41, 32
	s_cbranch_scc1 .Lbs_u19
	v_cndmask_b32_e64 v46, 0, v36, s[52:53]
	v_or_b32_e32 v30, v30, v46
	v_xor_b32_e32 v46, v26, v46
	v_cndmask_b32_e64 v26, v46, v36, s[50:51]
	v_and_b32_e32 v22, v26, v86
	v_cndmask_b32_e64 v46, 0, v22, s[22:23]
	v_or_b32_e32 v30, v30, v46
	v_xor_b32_e32 v46, v26, v46
	v_cndmask_b32_e64 v26, v46, v22, s[0:1]
	s_cmp_lt_i32 s41, 48
	s_cbranch_scc1 .Lbs_u19
	v_cndmask_b32_e64 v46, 0, v37, s[52:53]
	v_or_b32_e32 v31, v31, v46
	v_xor_b32_e32 v46, v27, v46
	v_cndmask_b32_e64 v27, v46, v37, s[50:51]
	v_and_b32_e32 v22, v27, v34
	v_cndmask_b32_e64 v46, 0, v22, s[22:23]
	v_or_b32_e32 v31, v31, v46
	v_xor_b32_e32 v46, v27, v46
	v_cndmask_b32_e64 v27, v46, v22, s[0:1]
.Lbs_u19:
	s_andn2_b64 s[48:49], exec, s[44:45]
	s_cbranch_scc0 .Lbs_end
	v_and_b32_e32 v32, v24, v166
	v_bcnt_u32_b32 v42, v32, v45
	v_and_b32_e32 v22, v24, v149
	v_and_b32_e32 v23, v32, v22
	v_bcnt_u32_b32 v43, v23, v45
	v_or_b32_e32 v23, v32, v22
	v_bcnt_u32_b32 v44, v23, v45
	s_cmp_lt_i32 s41, 16
	s_cbranch_scc1 .Lbs_c17
	v_and_b32_e32 v33, v25, v191
	v_bcnt_u32_b32 v42, v33, v42
	v_and_b32_e32 v22, v25, v181
	v_and_b32_e32 v23, v33, v22
	v_bcnt_u32_b32 v43, v23, v43
	v_or_b32_e32 v23, v33, v22
	v_bcnt_u32_b32 v44, v23, v44
	s_cmp_lt_i32 s41, 32
	s_cbranch_scc1 .Lbs_c17
	v_and_b32_e32 v36, v26, v87
	v_bcnt_u32_b32 v42, v36, v42
	v_and_b32_e32 v22, v26, v93
	v_and_b32_e32 v23, v36, v22
	v_bcnt_u32_b32 v43, v23, v43
	v_or_b32_e32 v23, v36, v22
	v_bcnt_u32_b32 v44, v23, v44
	s_cmp_lt_i32 s41, 48
	s_cbranch_scc1 .Lbs_c17
	v_and_b32_e32 v37, v27, v35
	v_bcnt_u32_b32 v42, v37, v42
	v_and_b32_e32 v22, v27, v57
	v_and_b32_e32 v23, v37, v22
	v_bcnt_u32_b32 v43, v23, v43
	v_or_b32_e32 v23, v37, v22
	v_bcnt_u32_b32 v44, v23, v44
; DI void a1_task(unsigned char* shm, const bf16_t* prm, const bf16_t* prt, unsigned* mask, int b, int qt, const int tid) {
;     ...
;             const unsigned cand = T | (1u << bit);
;             int c = 0;
; #pragma unroll
;             for (int jt = 0; jt < 8; ++jt) {
;                 if (jt < nheld) {
; #pragma unroll
;                     for (int i = 0; i < 16; ++i) c += (key[jt][i] >= cand) ? 1 : 0;
;                 }
;             }
;             c += __shfl_xor(c, 32);
;             if (h == 0 && c) atomicAdd(&cnt[(31 - bit) * 32 + r], (unsigned)c);
;             __syncthreads();
;             const unsigned tot = cnt[(31 - bit) * 32 + r];
;             if (!done) { if (tot >= 256u) T = cand; if (tot == 256u) done = true; }
;             if (__ballot(!done) == 0ull) break;
;         }
;     }
.Lbs_c17:
	v_lshl_or_b32 v38, v43, 16, v42
	v_mov_b32_e32 v39, v44
	v_mov_b32_e32 v40, v38
	v_mov_b32_e32 v41, v39
	s_nop 1
	v_permlane32_swap_b32_e32 v38, v40
	v_permlane32_swap_b32_e32 v39, v41
	v_add_u32_e32 v38, v38, v40
	v_add_u32_e32 v39, v39, v41
	v_or_b32_e32 v22, v38, v39
	v_cmp_ne_u32_e32 vcc, 0, v22
	s_and_b64 vcc, vcc, s[58:59]
	s_and_saveexec_b64 s[54:55], vcc
	ds_add_u64 v48, v[38:39] offset:1792
	s_mov_b64 exec, s[54:55]
	s_waitcnt lgkmcnt(0)
	s_barrier
	ds_read_b64 v[40:41], v48 offset:1792
	s_waitcnt lgkmcnt(0)
	v_and_b32_e32 v22, s6, v40
	v_lshrrev_b32_e32 v23, 16, v40
	v_cmp_lt_u32_e64 s[48:49], s42, v22
	v_cmp_eq_u32_e32 vcc, s43, v22
	s_andn2_b64 s[50:51], s[48:49], s[44:45]
	s_or_b64 s[48:49], s[48:49], s[44:45]
	s_andn2_b64 s[52:53], exec, s[48:49]
	s_or_b64 s[44:45], s[44:45], vcc
	v_cndmask_b32_e64 v49, v41, v23, s[50:51]
	v_cndmask_b32_e64 v46, v44, v43, s[50:51]
	v_cndmask_b32_e64 v45, v45, v42, s[52:53]
	v_cmp_lt_u32_e64 s[48:49], s42, v49
	v_cmp_eq_u32_e32 vcc, s43, v49
	s_andn2_b64 s[0:1], s[48:49], s[44:45]
	s_or_b64 s[48:49], s[48:49], s[44:45]
	s_andn2_b64 s[22:23], exec, s[48:49]
	s_or_b64 s[44:45], s[44:45], vcc
	s_or_b64 s[46:47], s[46:47], s[50:51]
	s_or_b64 s[46:47], s[46:47], s[0:1]
	v_cndmask_b32_e64 v45, v45, v46, s[22:23]
	v_cndmask_b32_e64 v46, 0, v32, s[52:53]
	v_or_b32_e32 v28, v28, v46
	v_xor_b32_e32 v46, v24, v46
	v_cndmask_b32_e64 v24, v46, v32, s[50:51]
	v_and_b32_e32 v22, v24, v149
	v_cndmask_b32_e64 v46, 0, v22, s[22:23]
	v_or_b32_e32 v28, v28, v46
	v_xor_b32_e32 v46, v24, v46
	v_cndmask_b32_e64 v24, v46, v22, s[0:1]
	s_cmp_lt_i32 s41, 16
	s_cbranch_scc1 .Lbs_u17
	v_cndmask_b32_e64 v46, 0, v33, s[52:53]
	v_or_b32_e32 v29, v29, v46
	v_xor_b32_e32 v46, v25, v46
	v_cndmask_b32_e64 v25, v46, v33, s[50:51]
	v_and_b32_e32 v22, v25, v181
	v_cndmask_b32_e64 v46, 0, v22, s[22:23]
	v_or_b32_e32 v29, v29, v46
	v_xor_b32_e32 v46, v25, v46
	v_cndmask_b32_e64 v25, v46, v22, s[0:1]
	s_cmp_lt_i32 s41, 32
	s_cbranch_scc1 .Lbs_u17
	v_cndmask_b32_e64 v46, 0, v36, s[52:53]
	v_or_b32_e32 v30, v30, v46
	v_xor_b32_e32 v46, v26, v46
	v_cndmask_b32_e64 v26, v46, v36, s[50:51]
	v_and_b32_e32 v22, v26, v93
	v_cndmask_b32_e64 v46, 0, v22, s[22:23]
	v_or_b32_e32 v30, v30, v46
	v_xor_b32_e32 v46, v26, v46
	v_cndmask_b32_e64 v26, v46, v22, s[0:1]
	s_cmp_lt_i32 s41, 48
	s_cbranch_scc1 .Lbs_u17
	v_cndmask_b32_e64 v46, 0, v37, s[52:53]
	v_or_b32_e32 v31, v31, v46
	v_xor_b32_e32 v46, v27, v46
	v_cndmask_b32_e64 v27, v46, v37, s[50:51]
	v_and_b32_e32 v22, v27, v57
	v_cndmask_b32_e64 v46, 0, v22, s[22:23]
	v_or_b32_e32 v31, v31, v46
	v_xor_b32_e32 v46, v27, v46
	v_cndmask_b32_e64 v27, v46, v22, s[0:1]
.Lbs_u17:
	s_andn2_b64 s[48:49], exec, s[44:45]
	s_cbranch_scc0 .Lbs_end
	v_and_b32_e32 v32, v24, v157
	v_bcnt_u32_b32 v42, v32, v45
	v_and_b32_e32 v22, v24, v154
	v_and_b32_e32 v23, v32, v22
	v_bcnt_u32_b32 v43, v23, v45
	v_or_b32_e32 v23, v32, v22
	v_bcnt_u32_b32 v44, v23, v45
	s_cmp_lt_i32 s41, 16
	s_cbranch_scc1 .Lbs_c15
	v_and_b32_e32 v33, v25, v189
	v_bcnt_u32_b32 v42, v33, v42
	v_and_b32_e32 v22, v25, v186
	v_and_b32_e32 v23, v33, v22
	v_bcnt_u32_b32 v43, v23, v43
	v_or_b32_e32 v23, v33, v22
	v_bcnt_u32_b32 v44, v23, v44
	s_cmp_lt_i32 s41, 32
	s_cbranch_scc1 .Lbs_c15
	v_and_b32_e32 v36, v26, v230
	v_bcnt_u32_b32 v42, v36, v42
	v_and_b32_e32 v22, v26, v227
	v_and_b32_e32 v23, v36, v22
	v_bcnt_u32_b32 v43, v23, v43
	v_or_b32_e32 v23, v36, v22
	v_bcnt_u32_b32 v44, v23, v44
	s_cmp_lt_i32 s41, 48
	s_cbranch_scc1 .Lbs_c15
	v_and_b32_e32 v37, v27, v65
	v_bcnt_u32_b32 v42, v37, v42
	v_and_b32_e32 v22, v27, v62
	v_and_b32_e32 v23, v37, v22
	v_bcnt_u32_b32 v43, v23, v43
	v_or_b32_e32 v23, v37, v22
	v_bcnt_u32_b32 v44, v23, v44
.Lbs_c15:
	v_lshl_or_b32 v38, v43, 16, v42
	v_mov_b32_e32 v39, v44
	v_mov_b32_e32 v40, v38
	v_mov_b32_e32 v41, v39
	s_nop 1
	v_permlane32_swap_b32_e32 v38, v40
	v_permlane32_swap_b32_e32 v39, v41
	v_add_u32_e32 v38, v38, v40
	v_add_u32_e32 v39, v39, v41
	v_or_b32_e32 v22, v38, v39
	v_cmp_ne_u32_e32 vcc, 0, v22
	s_and_b64 vcc, vcc, s[58:59]
	s_and_saveexec_b64 s[54:55], vcc
	ds_add_u64 v48, v[38:39] offset:2048
	s_mov_b64 exec, s[54:55]
	s_waitcnt lgkmcnt(0)
	s_barrier
	ds_read_b64 v[40:41], v48 offset:2048
	s_waitcnt lgkmcnt(0)
	v_and_b32_e32 v22, s6, v40
	v_lshrrev_b32_e32 v23, 16, v40
	v_cmp_lt_u32_e64 s[48:49], s42, v22
	v_cmp_eq_u32_e32 vcc, s43, v22
	s_andn2_b64 s[50:51], s[48:49], s[44:45]
	s_or_b64 s[48:49], s[48:49], s[44:45]
	s_andn2_b64 s[52:53], exec, s[48:49]
	s_or_b64 s[44:45], s[44:45], vcc
	v_cndmask_b32_e64 v49, v41, v23, s[50:51]
	v_cndmask_b32_e64 v46, v44, v43, s[50:51]
	v_cndmask_b32_e64 v45, v45, v42, s[52:53]
	v_cmp_lt_u32_e64 s[48:49], s42, v49
	v_cmp_eq_u32_e32 vcc, s43, v49
	s_andn2_b64 s[0:1], s[48:49], s[44:45]
	s_or_b64 s[48:49], s[48:49], s[44:45]
	s_andn2_b64 s[22:23], exec, s[48:49]
	s_or_b64 s[44:45], s[44:45], vcc
	s_or_b64 s[46:47], s[46:47], s[50:51]
	s_or_b64 s[46:47], s[46:47], s[0:1]
	v_cndmask_b32_e64 v45, v45, v46, s[22:23]
	v_cndmask_b32_e64 v46, 0, v32, s[52:53]
	v_or_b32_e32 v28, v28, v46
	v_xor_b32_e32 v46, v24, v46
	v_cndmask_b32_e64 v24, v46, v32, s[50:51]
	v_and_b32_e32 v22, v24, v154
	v_cndmask_b32_e64 v46, 0, v22, s[22:23]
	v_or_b32_e32 v28, v28, v46
	v_xor_b32_e32 v46, v24, v46
	v_cndmask_b32_e64 v24, v46, v22, s[0:1]
	s_cmp_lt_i32 s41, 16
	s_cbranch_scc1 .Lbs_u15
	v_cndmask_b32_e64 v46, 0, v33, s[52:53]
	v_or_b32_e32 v29, v29, v46
	v_xor_b32_e32 v46, v25, v46
	v_cndmask_b32_e64 v25, v46, v33, s[50:51]
	v_and_b32_e32 v22, v25, v186
	v_cndmask_b32_e64 v46, 0, v22, s[22:23]
	v_or_b32_e32 v29, v29, v46
	v_xor_b32_e32 v46, v25, v46
	v_cndmask_b32_e64 v25, v46, v22, s[0:1]
	s_cmp_lt_i32 s41, 32
	s_cbranch_scc1 .Lbs_u15
	v_cndmask_b32_e64 v46, 0, v36, s[52:53]
	v_or_b32_e32 v30, v30, v46
	v_xor_b32_e32 v46, v26, v46
	v_cndmask_b32_e64 v26, v46, v36, s[50:51]
	v_and_b32_e32 v22, v26, v227
	v_cndmask_b32_e64 v46, 0, v22, s[22:23]
	v_or_b32_e32 v30, v30, v46
	v_xor_b32_e32 v46, v26, v46
	v_cndmask_b32_e64 v26, v46, v22, s[0:1]
	s_cmp_lt_i32 s41, 48
	s_cbranch_scc1 .Lbs_u15
	v_cndmask_b32_e64 v46, 0, v37, s[52:53]
	v_or_b32_e32 v31, v31, v46
	v_xor_b32_e32 v46, v27, v46
	v_cndmask_b32_e64 v27, v46, v37, s[50:51]
	v_and_b32_e32 v22, v27, v62
	v_cndmask_b32_e64 v46, 0, v22, s[22:23]
	v_or_b32_e32 v31, v31, v46
	v_xor_b32_e32 v46, v27, v46
	v_cndmask_b32_e64 v27, v46, v22, s[0:1]
; DI void a1_task(unsigned char* shm, const bf16_t* prm, const bf16_t* prt, unsigned* mask, int b, int qt, const int tid) {
;     ...
;             const unsigned cand = T | (1u << bit);
;             int c = 0;
; #pragma unroll
;             for (int jt = 0; jt < 8; ++jt) {
;                 if (jt < nheld) {
; #pragma unroll
;                     for (int i = 0; i < 16; ++i) c += (key[jt][i] >= cand) ? 1 : 0;
;                 }
;             }
;             c += __shfl_xor(c, 32);
;             if (h == 0 && c) atomicAdd(&cnt[(31 - bit) * 32 + r], (unsigned)c);
;             __syncthreads();
;             const unsigned tot = cnt[(31 - bit) * 32 + r];
;             if (!done) { if (tot >= 256u) T = cand; if (tot == 256u) done = true; }
;             if (__ballot(!done) == 0ull) break;
;         }
;     }
.Lbs_u15:
	s_andn2_b64 s[48:49], exec, s[44:45]
	s_cbranch_scc0 .Lbs_end
	v_and_b32_e32 v32, v24, v155
	v_bcnt_u32_b32 v42, v32, v45
	v_and_b32_e32 v22, v24, v152
	v_and_b32_e32 v23, v32, v22
	v_bcnt_u32_b32 v43, v23, v45
	v_or_b32_e32 v23, v32, v22
	v_bcnt_u32_b32 v44, v23, v45
	s_cmp_lt_i32 s41, 16
	s_cbranch_scc1 .Lbs_c13
	v_and_b32_e32 v33, v25, v187
	v_bcnt_u32_b32 v42, v33, v42
	v_and_b32_e32 v22, v25, v184
	v_and_b32_e32 v23, v33, v22
	v_bcnt_u32_b32 v43, v23, v43
	v_or_b32_e32 v23, v33, v22
	v_bcnt_u32_b32 v44, v23, v44
	s_cmp_lt_i32 s41, 32
	s_cbranch_scc1 .Lbs_c13
	v_and_b32_e32 v36, v26, v228
	v_bcnt_u32_b32 v42, v36, v42
	v_and_b32_e32 v22, v26, v225
	v_and_b32_e32 v23, v36, v22
	v_bcnt_u32_b32 v43, v23, v43
	v_or_b32_e32 v23, v36, v22
	v_bcnt_u32_b32 v44, v23, v44
	s_cmp_lt_i32 s41, 48
	s_cbranch_scc1 .Lbs_c13
	v_and_b32_e32 v37, v27, v63
	v_bcnt_u32_b32 v42, v37, v42
	v_and_b32_e32 v22, v27, v60
	v_and_b32_e32 v23, v37, v22
	v_bcnt_u32_b32 v43, v23, v43
	v_or_b32_e32 v23, v37, v22
	v_bcnt_u32_b32 v44, v23, v44
.Lbs_c13:
	v_lshl_or_b32 v38, v43, 16, v42
	v_mov_b32_e32 v39, v44
	v_mov_b32_e32 v40, v38
	v_mov_b32_e32 v41, v39
	s_nop 1
	v_permlane32_swap_b32_e32 v38, v40
	v_permlane32_swap_b32_e32 v39, v41
	v_add_u32_e32 v38, v38, v40
	v_add_u32_e32 v39, v39, v41
	v_or_b32_e32 v22, v38, v39
	v_cmp_ne_u32_e32 vcc, 0, v22
	s_and_b64 vcc, vcc, s[58:59]
	s_and_saveexec_b64 s[54:55], vcc
	ds_add_u64 v48, v[38:39] offset:2304
	s_mov_b64 exec, s[54:55]
	s_waitcnt lgkmcnt(0)
	s_barrier
	ds_read_b64 v[40:41], v48 offset:2304
	s_waitcnt lgkmcnt(0)
	v_and_b32_e32 v22, s6, v40
	v_lshrrev_b32_e32 v23, 16, v40
	v_cmp_lt_u32_e64 s[48:49], s42, v22
	v_cmp_eq_u32_e32 vcc, s43, v22
	s_andn2_b64 s[50:51], s[48:49], s[44:45]
	s_or_b64 s[48:49], s[48:49], s[44:45]
	s_andn2_b64 s[52:53], exec, s[48:49]
	s_or_b64 s[44:45], s[44:45], vcc
	v_cndmask_b32_e64 v49, v41, v23, s[50:51]
	v_cndmask_b32_e64 v46, v44, v43, s[50:51]
	v_cndmask_b32_e64 v45, v45, v42, s[52:53]
	v_cmp_lt_u32_e64 s[48:49], s42, v49
	v_cmp_eq_u32_e32 vcc, s43, v49
	s_andn2_b64 s[0:1], s[48:49], s[44:45]
	s_or_b64 s[48:49], s[48:49], s[44:45]
	s_andn2_b64 s[22:23], exec, s[48:49]
	s_or_b64 s[44:45], s[44:45], vcc
	s_or_b64 s[46:47], s[46:47], s[50:51]
	s_or_b64 s[46:47], s[46:47], s[0:1]
	v_cndmask_b32_e64 v45, v45, v46, s[22:23]
	v_cndmask_b32_e64 v46, 0, v32, s[52:53]
	v_or_b32_e32 v28, v28, v46
	v_xor_b32_e32 v46, v24, v46
	v_cndmask_b32_e64 v24, v46, v32, s[50:51]
	v_and_b32_e32 v22, v24, v152
	v_cndmask_b32_e64 v46, 0, v22, s[22:23]
	v_or_b32_e32 v28, v28, v46
	v_xor_b32_e32 v46, v24, v46
	v_cndmask_b32_e64 v24, v46, v22, s[0:1]
	s_cmp_lt_i32 s41, 16
	s_cbranch_scc1 .Lbs_u13
	v_cndmask_b32_e64 v46, 0, v33, s[52:53]
	v_or_b32_e32 v29, v29, v46
	v_xor_b32_e32 v46, v25, v46
	v_cndmask_b32_e64 v25, v46, v33, s[50:51]
	v_and_b32_e32 v22, v25, v184
	v_cndmask_b32_e64 v46, 0, v22, s[22:23]
	v_or_b32_e32 v29, v29, v46
	v_xor_b32_e32 v46, v25, v46
	v_cndmask_b32_e64 v25, v46, v22, s[0:1]
	s_cmp_lt_i32 s41, 32
	s_cbranch_scc1 .Lbs_u13
	v_cndmask_b32_e64 v46, 0, v36, s[52:53]
	v_or_b32_e32 v30, v30, v46
	v_xor_b32_e32 v46, v26, v46
	v_cndmask_b32_e64 v26, v46, v36, s[50:51]
	v_and_b32_e32 v22, v26, v225
	v_cndmask_b32_e64 v46, 0, v22, s[22:23]
	v_or_b32_e32 v30, v30, v46
	v_xor_b32_e32 v46, v26, v46
	v_cndmask_b32_e64 v26, v46, v22, s[0:1]
	s_cmp_lt_i32 s41, 48
	s_cbranch_scc1 .Lbs_u13
	v_cndmask_b32_e64 v46, 0, v37, s[52:53]
	v_or_b32_e32 v31, v31, v46
	v_xor_b32_e32 v46, v27, v46
	v_cndmask_b32_e64 v27, v46, v37, s[50:51]
	v_and_b32_e32 v22, v27, v60
	v_cndmask_b32_e64 v46, 0, v22, s[22:23]
	v_or_b32_e32 v31, v31, v46
	v_xor_b32_e32 v46, v27, v46
	v_cndmask_b32_e64 v27, v46, v22, s[0:1]
.Lbs_u13:
	s_andn2_b64 s[48:49], exec, s[44:45]
	s_cbranch_scc0 .Lbs_end
	v_and_b32_e32 v32, v24, v153
	v_bcnt_u32_b32 v42, v32, v45
	v_and_b32_e32 v22, v24, v150
	v_and_b32_e32 v23, v32, v22
	v_bcnt_u32_b32 v43, v23, v45
	v_or_b32_e32 v23, v32, v22
	v_bcnt_u32_b32 v44, v23, v45
	s_cmp_lt_i32 s41, 16
	s_cbranch_scc1 .Lbs_c11
	v_and_b32_e32 v33, v25, v185
	v_bcnt_u32_b32 v42, v33, v42
	v_and_b32_e32 v22, v25, v182
	v_and_b32_e32 v23, v33, v22
	v_bcnt_u32_b32 v43, v23, v43
	v_or_b32_e32 v23, v33, v22
	v_bcnt_u32_b32 v44, v23, v44
	s_cmp_lt_i32 s41, 32
	s_cbranch_scc1 .Lbs_c11
	v_and_b32_e32 v36, v26, v226
	v_bcnt_u32_b32 v42, v36, v42
	v_and_b32_e32 v22, v26, v223
	v_and_b32_e32 v23, v36, v22
	v_bcnt_u32_b32 v43, v23, v43
	v_or_b32_e32 v23, v36, v22
	v_bcnt_u32_b32 v44, v23, v44
	s_cmp_lt_i32 s41, 48
	s_cbranch_scc1 .Lbs_c11
	v_and_b32_e32 v37, v27, v61
	v_bcnt_u32_b32 v42, v37, v42
	v_and_b32_e32 v22, v27, v58
	v_and_b32_e32 v23, v37, v22
	v_bcnt_u32_b32 v43, v23, v43
	v_or_b32_e32 v23, v37, v22
	v_bcnt_u32_b32 v44, v23, v44
; DI void a1_task(unsigned char* shm, const bf16_t* prm, const bf16_t* prt, unsigned* mask, int b, int qt, const int tid) {
;     ...
;             const unsigned cand = T | (1u << bit);
;             int c = 0;
; #pragma unroll
;             for (int jt = 0; jt < 8; ++jt) {
;                 if (jt < nheld) {
; #pragma unroll
;                     for (int i = 0; i < 16; ++i) c += (key[jt][i] >= cand) ? 1 : 0;
;                 }
;             }
;             c += __shfl_xor(c, 32);
;             if (h == 0 && c) atomicAdd(&cnt[(31 - bit) * 32 + r], (unsigned)c);
;             __syncthreads();
;             const unsigned tot = cnt[(31 - bit) * 32 + r];
;             if (!done) { if (tot >= 256u) T = cand; if (tot == 256u) done = true; }
;             if (__ballot(!done) == 0ull) break;
;         }
;     }
.Lbs_c11:
	v_lshl_or_b32 v38, v43, 16, v42
	v_mov_b32_e32 v39, v44
	v_mov_b32_e32 v40, v38
	v_mov_b32_e32 v41, v39
	s_nop 1
	v_permlane32_swap_b32_e32 v38, v40
	v_permlane32_swap_b32_e32 v39, v41
	v_add_u32_e32 v38, v38, v40
	v_add_u32_e32 v39, v39, v41
	v_or_b32_e32 v22, v38, v39
	v_cmp_ne_u32_e32 vcc, 0, v22
	s_and_b64 vcc, vcc, s[58:59]
	s_and_saveexec_b64 s[54:55], vcc
	ds_add_u64 v48, v[38:39] offset:2560
	s_mov_b64 exec, s[54:55]
	s_waitcnt lgkmcnt(0)
	s_barrier
	ds_read_b64 v[40:41], v48 offset:2560
	s_waitcnt lgkmcnt(0)
	v_and_b32_e32 v22, s6, v40
	v_lshrrev_b32_e32 v23, 16, v40
	v_cmp_lt_u32_e64 s[48:49], s42, v22
	v_cmp_eq_u32_e32 vcc, s43, v22
	s_andn2_b64 s[50:51], s[48:49], s[44:45]
	s_or_b64 s[48:49], s[48:49], s[44:45]
	s_andn2_b64 s[52:53], exec, s[48:49]
	s_or_b64 s[44:45], s[44:45], vcc
	v_cndmask_b32_e64 v49, v41, v23, s[50:51]
	v_cndmask_b32_e64 v46, v44, v43, s[50:51]
	v_cndmask_b32_e64 v45, v45, v42, s[52:53]
	v_cmp_lt_u32_e64 s[48:49], s42, v49
	v_cmp_eq_u32_e32 vcc, s43, v49
	s_andn2_b64 s[0:1], s[48:49], s[44:45]
	s_or_b64 s[48:49], s[48:49], s[44:45]
	s_andn2_b64 s[22:23], exec, s[48:49]
	s_or_b64 s[44:45], s[44:45], vcc
	s_or_b64 s[46:47], s[46:47], s[50:51]
	s_or_b64 s[46:47], s[46:47], s[0:1]
	v_cndmask_b32_e64 v45, v45, v46, s[22:23]
	v_cndmask_b32_e64 v46, 0, v32, s[52:53]
	v_or_b32_e32 v28, v28, v46
	v_xor_b32_e32 v46, v24, v46
	v_cndmask_b32_e64 v24, v46, v32, s[50:51]
	v_and_b32_e32 v22, v24, v150
	v_cndmask_b32_e64 v46, 0, v22, s[22:23]
	v_or_b32_e32 v28, v28, v46
	v_xor_b32_e32 v46, v24, v46
	v_cndmask_b32_e64 v24, v46, v22, s[0:1]
	s_cmp_lt_i32 s41, 16
	s_cbranch_scc1 .Lbs_u11
	v_cndmask_b32_e64 v46, 0, v33, s[52:53]
	v_or_b32_e32 v29, v29, v46
	v_xor_b32_e32 v46, v25, v46
	v_cndmask_b32_e64 v25, v46, v33, s[50:51]
	v_and_b32_e32 v22, v25, v182
	v_cndmask_b32_e64 v46, 0, v22, s[22:23]
	v_or_b32_e32 v29, v29, v46
	v_xor_b32_e32 v46, v25, v46
	v_cndmask_b32_e64 v25, v46, v22, s[0:1]
	s_cmp_lt_i32 s41, 32
	s_cbranch_scc1 .Lbs_u11
	v_cndmask_b32_e64 v46, 0, v36, s[52:53]
	v_or_b32_e32 v30, v30, v46
	v_xor_b32_e32 v46, v26, v46
	v_cndmask_b32_e64 v26, v46, v36, s[50:51]
	v_and_b32_e32 v22, v26, v223
	v_cndmask_b32_e64 v46, 0, v22, s[22:23]
	v_or_b32_e32 v30, v30, v46
	v_xor_b32_e32 v46, v26, v46
	v_cndmask_b32_e64 v26, v46, v22, s[0:1]
	s_cmp_lt_i32 s41, 48
	s_cbranch_scc1 .Lbs_u11
	v_cndmask_b32_e64 v46, 0, v37, s[52:53]
	v_or_b32_e32 v31, v31, v46
	v_xor_b32_e32 v46, v27, v46
	v_cndmask_b32_e64 v27, v46, v37, s[50:51]
	v_and_b32_e32 v22, v27, v58
	v_cndmask_b32_e64 v46, 0, v22, s[22:23]
	v_or_b32_e32 v31, v31, v46
	v_xor_b32_e32 v46, v27, v46
	v_cndmask_b32_e64 v27, v46, v22, s[0:1]
.Lbs_u11:
	s_andn2_b64 s[48:49], exec, s[44:45]
	s_cbranch_scc0 .Lbs_end
	v_and_b32_e32 v32, v24, v151
	v_bcnt_u32_b32 v42, v32, v45
	v_and_b32_e32 v22, v24, v147
	v_and_b32_e32 v23, v32, v22
	v_bcnt_u32_b32 v43, v23, v45
	v_or_b32_e32 v23, v32, v22
	v_bcnt_u32_b32 v44, v23, v45
	s_cmp_lt_i32 s41, 16
	s_cbranch_scc1 .Lbs_c9
	v_and_b32_e32 v33, v25, v183
	v_bcnt_u32_b32 v42, v33, v42
	v_and_b32_e32 v22, v25, v180
	v_and_b32_e32 v23, v33, v22
	v_bcnt_u32_b32 v43, v23, v43
	v_or_b32_e32 v23, v33, v22
	v_bcnt_u32_b32 v44, v23, v44
	s_cmp_lt_i32 s41, 32
	s_cbranch_scc1 .Lbs_c9
	v_and_b32_e32 v36, v26, v224
	v_bcnt_u32_b32 v42, v36, v42
	v_and_b32_e32 v22, v26, v92
	v_and_b32_e32 v23, v36, v22
	v_bcnt_u32_b32 v43, v23, v43
	v_or_b32_e32 v23, v36, v22
	v_bcnt_u32_b32 v44, v23, v44
	s_cmp_lt_i32 s41, 48
	s_cbranch_scc1 .Lbs_c9
	v_and_b32_e32 v37, v27, v59
	v_bcnt_u32_b32 v42, v37, v42
	v_and_b32_e32 v22, v27, v56
	v_and_b32_e32 v23, v37, v22
	v_bcnt_u32_b32 v43, v23, v43
	v_or_b32_e32 v23, v37, v22
	v_bcnt_u32_b32 v44, v23, v44
.Lbs_c9:
	v_lshl_or_b32 v38, v43, 16, v42
	v_mov_b32_e32 v39, v44
	v_mov_b32_e32 v40, v38
	v_mov_b32_e32 v41, v39
	s_nop 1
	v_permlane32_swap_b32_e32 v38, v40
	v_permlane32_swap_b32_e32 v39, v41
	v_add_u32_e32 v38, v38, v40
	v_add_u32_e32 v39, v39, v41
	v_or_b32_e32 v22, v38, v39
	v_cmp_ne_u32_e32 vcc, 0, v22
	s_and_b64 vcc, vcc, s[58:59]
	s_and_saveexec_b64 s[54:55], vcc
	ds_add_u64 v48, v[38:39] offset:2816
	s_mov_b64 exec, s[54:55]
	s_waitcnt lgkmcnt(0)
	s_barrier
	ds_read_b64 v[40:41], v48 offset:2816
	s_waitcnt lgkmcnt(0)
	v_and_b32_e32 v22, s6, v40
	v_lshrrev_b32_e32 v23, 16, v40
	v_cmp_lt_u32_e64 s[48:49], s42, v22
	v_cmp_eq_u32_e32 vcc, s43, v22
	s_andn2_b64 s[50:51], s[48:49], s[44:45]
	s_or_b64 s[48:49], s[48:49], s[44:45]
	s_andn2_b64 s[52:53], exec, s[48:49]
	s_or_b64 s[44:45], s[44:45], vcc
	v_cndmask_b32_e64 v49, v41, v23, s[50:51]
	v_cndmask_b32_e64 v46, v44, v43, s[50:51]
	v_cndmask_b32_e64 v45, v45, v42, s[52:53]
	v_cmp_lt_u32_e64 s[48:49], s42, v49
	v_cmp_eq_u32_e32 vcc, s43, v49
	s_andn2_b64 s[0:1], s[48:49], s[44:45]
	s_or_b64 s[48:49], s[48:49], s[44:45]
	s_andn2_b64 s[22:23], exec, s[48:49]
	s_or_b64 s[44:45], s[44:45], vcc
	s_or_b64 s[46:47], s[46:47], s[50:51]
	s_or_b64 s[46:47], s[46:47], s[0:1]
	v_cndmask_b32_e64 v45, v45, v46, s[22:23]
	v_cndmask_b32_e64 v46, 0, v32, s[52:53]
	v_or_b32_e32 v28, v28, v46
	v_xor_b32_e32 v46, v24, v46
	v_cndmask_b32_e64 v24, v46, v32, s[50:51]
	v_and_b32_e32 v22, v24, v147
	v_cndmask_b32_e64 v46, 0, v22, s[22:23]
	v_or_b32_e32 v28, v28, v46
	v_xor_b32_e32 v46, v24, v46
	v_cndmask_b32_e64 v24, v46, v22, s[0:1]
	s_cmp_lt_i32 s41, 16
	s_cbranch_scc1 .Lbs_u9
	v_cndmask_b32_e64 v46, 0, v33, s[52:53]
	v_or_b32_e32 v29, v29, v46
	v_xor_b32_e32 v46, v25, v46
	v_cndmask_b32_e64 v25, v46, v33, s[50:51]
	v_and_b32_e32 v22, v25, v180
	v_cndmask_b32_e64 v46, 0, v22, s[22:23]
	v_or_b32_e32 v29, v29, v46
	v_xor_b32_e32 v46, v25, v46
	v_cndmask_b32_e64 v25, v46, v22, s[0:1]
	s_cmp_lt_i32 s41, 32
	s_cbranch_scc1 .Lbs_u9
	v_cndmask_b32_e64 v46, 0, v36, s[52:53]
	v_or_b32_e32 v30, v30, v46
	v_xor_b32_e32 v46, v26, v46
	v_cndmask_b32_e64 v26, v46, v36, s[50:51]
	v_and_b32_e32 v22, v26, v92
	v_cndmask_b32_e64 v46, 0, v22, s[22:23]
	v_or_b32_e32 v30, v30, v46
	v_xor_b32_e32 v46, v26, v46
	v_cndmask_b32_e64 v26, v46, v22, s[0:1]
	s_cmp_lt_i32 s41, 48
	s_cbranch_scc1 .Lbs_u9
	v_cndmask_b32_e64 v46, 0, v37, s[52:53]
	v_or_b32_e32 v31, v31, v46
	v_xor_b32_e32 v46, v27, v46
	v_cndmask_b32_e64 v27, v46, v37, s[50:51]
	v_and_b32_e32 v22, v27, v56
	v_cndmask_b32_e64 v46, 0, v22, s[22:23]
	v_or_b32_e32 v31, v31, v46
	v_xor_b32_e32 v46, v27, v46
	v_cndmask_b32_e64 v27, v46, v22, s[0:1]
; DI void a1_task(unsigned char* shm, const bf16_t* prm, const bf16_t* prt, unsigned* mask, int b, int qt, const int tid) {
;     ...
;             const unsigned cand = T | (1u << bit);
;             int c = 0;
; #pragma unroll
;             for (int jt = 0; jt < 8; ++jt) {
;                 if (jt < nheld) {
; #pragma unroll
;                     for (int i = 0; i < 16; ++i) c += (key[jt][i] >= cand) ? 1 : 0;
;                 }
;             }
;             c += __shfl_xor(c, 32);
;             if (h == 0 && c) atomicAdd(&cnt[(31 - bit) * 32 + r], (unsigned)c);
;             __syncthreads();
;             const unsigned tot = cnt[(31 - bit) * 32 + r];
;             if (!done) { if (tot >= 256u) T = cand; if (tot == 256u) done = true; }
;             if (__ballot(!done) == 0ull) break;
;         }
;     }
.Lbs_u9:
	s_andn2_b64 s[48:49], exec, s[44:45]
	s_cbranch_scc0 .Lbs_end
	v_and_b32_e32 v32, v24, v145
	v_bcnt_u32_b32 v42, v32, v45
	v_and_b32_e32 v22, v24, v146
	v_and_b32_e32 v23, v32, v22
	v_bcnt_u32_b32 v43, v23, v45
	v_or_b32_e32 v23, v32, v22
	v_bcnt_u32_b32 v44, v23, v45
	s_cmp_lt_i32 s41, 16
	s_cbranch_scc1 .Lbs_c7
	v_and_b32_e32 v33, v25, v178
	v_bcnt_u32_b32 v42, v33, v42
	v_and_b32_e32 v22, v25, v179
	v_and_b32_e32 v23, v33, v22
	v_bcnt_u32_b32 v43, v23, v43
	v_or_b32_e32 v23, v33, v22
	v_bcnt_u32_b32 v44, v23, v44
	s_cmp_lt_i32 s41, 32
	s_cbranch_scc1 .Lbs_c7
	v_and_b32_e32 v36, v26, v90
	v_bcnt_u32_b32 v42, v36, v42
	v_and_b32_e32 v22, v26, v91
	v_and_b32_e32 v23, v36, v22
	v_bcnt_u32_b32 v43, v23, v43
	v_or_b32_e32 v23, v36, v22
	v_bcnt_u32_b32 v44, v23, v44
	s_cmp_lt_i32 s41, 48
	s_cbranch_scc1 .Lbs_c7
	v_and_b32_e32 v37, v27, v54
	v_bcnt_u32_b32 v42, v37, v42
	v_and_b32_e32 v22, v27, v55
	v_and_b32_e32 v23, v37, v22
	v_bcnt_u32_b32 v43, v23, v43
	v_or_b32_e32 v23, v37, v22
	v_bcnt_u32_b32 v44, v23, v44
.Lbs_c7:
	v_lshl_or_b32 v38, v43, 16, v42
	v_mov_b32_e32 v39, v44
	v_mov_b32_e32 v40, v38
	v_mov_b32_e32 v41, v39
	s_nop 1
	v_permlane32_swap_b32_e32 v38, v40
	v_permlane32_swap_b32_e32 v39, v41
	v_add_u32_e32 v38, v38, v40
	v_add_u32_e32 v39, v39, v41
	v_or_b32_e32 v22, v38, v39
	v_cmp_ne_u32_e32 vcc, 0, v22
	s_and_b64 vcc, vcc, s[58:59]
	s_and_saveexec_b64 s[54:55], vcc
	ds_add_u64 v48, v[38:39] offset:3072
	s_mov_b64 exec, s[54:55]
	s_waitcnt lgkmcnt(0)
	s_barrier
	ds_read_b64 v[40:41], v48 offset:3072
	s_waitcnt lgkmcnt(0)
	v_and_b32_e32 v22, s6, v40
	v_lshrrev_b32_e32 v23, 16, v40
	v_cmp_lt_u32_e64 s[48:49], s42, v22
	v_cmp_eq_u32_e32 vcc, s43, v22
	s_andn2_b64 s[50:51], s[48:49], s[44:45]
	s_or_b64 s[48:49], s[48:49], s[44:45]
	s_andn2_b64 s[52:53], exec, s[48:49]
	s_or_b64 s[44:45], s[44:45], vcc
	v_cndmask_b32_e64 v49, v41, v23, s[50:51]
	v_cndmask_b32_e64 v46, v44, v43, s[50:51]
	v_cndmask_b32_e64 v45, v45, v42, s[52:53]
	v_cmp_lt_u32_e64 s[48:49], s42, v49
	v_cmp_eq_u32_e32 vcc, s43, v49
	s_andn2_b64 s[0:1], s[48:49], s[44:45]
	s_or_b64 s[48:49], s[48:49], s[44:45]
	s_andn2_b64 s[22:23], exec, s[48:49]
	s_or_b64 s[44:45], s[44:45], vcc
	s_or_b64 s[46:47], s[46:47], s[50:51]
	s_or_b64 s[46:47], s[46:47], s[0:1]
	v_cndmask_b32_e64 v45, v45, v46, s[22:23]
	v_cndmask_b32_e64 v46, 0, v32, s[52:53]
	v_or_b32_e32 v28, v28, v46
	v_xor_b32_e32 v46, v24, v46
	v_cndmask_b32_e64 v24, v46, v32, s[50:51]
	v_and_b32_e32 v22, v24, v146
	v_cndmask_b32_e64 v46, 0, v22, s[22:23]
	v_or_b32_e32 v28, v28, v46
	v_xor_b32_e32 v46, v24, v46
	v_cndmask_b32_e64 v24, v46, v22, s[0:1]
	s_cmp_lt_i32 s41, 16
	s_cbranch_scc1 .Lbs_u7
	v_cndmask_b32_e64 v46, 0, v33, s[52:53]
	v_or_b32_e32 v29, v29, v46
	v_xor_b32_e32 v46, v25, v46
	v_cndmask_b32_e64 v25, v46, v33, s[50:51]
	v_and_b32_e32 v22, v25, v179
	v_cndmask_b32_e64 v46, 0, v22, s[22:23]
	v_or_b32_e32 v29, v29, v46
	v_xor_b32_e32 v46, v25, v46
	v_cndmask_b32_e64 v25, v46, v22, s[0:1]
	s_cmp_lt_i32 s41, 32
	s_cbranch_scc1 .Lbs_u7
	v_cndmask_b32_e64 v46, 0, v36, s[52:53]
	v_or_b32_e32 v30, v30, v46
	v_xor_b32_e32 v46, v26, v46
	v_cndmask_b32_e64 v26, v46, v36, s[50:51]
	v_and_b32_e32 v22, v26, v91
	v_cndmask_b32_e64 v46, 0, v22, s[22:23]
	v_or_b32_e32 v30, v30, v46
	v_xor_b32_e32 v46, v26, v46
	v_cndmask_b32_e64 v26, v46, v22, s[0:1]
	s_cmp_lt_i32 s41, 48
	s_cbranch_scc1 .Lbs_u7
	v_cndmask_b32_e64 v46, 0, v37, s[52:53]
	v_or_b32_e32 v31, v31, v46
	v_xor_b32_e32 v46, v27, v46
	v_cndmask_b32_e64 v27, v46, v37, s[50:51]
	v_and_b32_e32 v22, v27, v55
	v_cndmask_b32_e64 v46, 0, v22, s[22:23]
	v_or_b32_e32 v31, v31, v46
	v_xor_b32_e32 v46, v27, v46
	v_cndmask_b32_e64 v27, v46, v22, s[0:1]
.Lbs_u7:
	s_andn2_b64 s[48:49], exec, s[44:45]
	s_cbranch_scc0 .Lbs_end
	v_and_b32_e32 v32, v24, v143
	v_bcnt_u32_b32 v42, v32, v45
	v_and_b32_e32 v22, v24, v144
	v_and_b32_e32 v23, v32, v22
	v_bcnt_u32_b32 v43, v23, v45
	v_or_b32_e32 v23, v32, v22
	v_bcnt_u32_b32 v44, v23, v45
	s_cmp_lt_i32 s41, 16
	s_cbranch_scc1 .Lbs_c5
	v_and_b32_e32 v33, v25, v176
	v_bcnt_u32_b32 v42, v33, v42
	v_and_b32_e32 v22, v25, v177
	v_and_b32_e32 v23, v33, v22
	v_bcnt_u32_b32 v43, v23, v43
	v_or_b32_e32 v23, v33, v22
	v_bcnt_u32_b32 v44, v23, v44
	s_cmp_lt_i32 s41, 32
	s_cbranch_scc1 .Lbs_c5
	v_and_b32_e32 v36, v26, v84
	v_bcnt_u32_b32 v42, v36, v42
	v_and_b32_e32 v22, v26, v85
	v_and_b32_e32 v23, v36, v22
	v_bcnt_u32_b32 v43, v23, v43
	v_or_b32_e32 v23, v36, v22
	v_bcnt_u32_b32 v44, v23, v44
	s_cmp_lt_i32 s41, 48
	s_cbranch_scc1 .Lbs_c5
	v_and_b32_e32 v37, v27, v52
	v_bcnt_u32_b32 v42, v37, v42
	v_and_b32_e32 v22, v27, v53
	v_and_b32_e32 v23, v37, v22
	v_bcnt_u32_b32 v43, v23, v43
	v_or_b32_e32 v23, v37, v22
	v_bcnt_u32_b32 v44, v23, v44
; DI void a1_task(unsigned char* shm, const bf16_t* prm, const bf16_t* prt, unsigned* mask, int b, int qt, const int tid) {
;     ...
;             const unsigned cand = T | (1u << bit);
;             int c = 0;
; #pragma unroll
;             for (int jt = 0; jt < 8; ++jt) {
;                 if (jt < nheld) {
; #pragma unroll
;                     for (int i = 0; i < 16; ++i) c += (key[jt][i] >= cand) ? 1 : 0;
;                 }
;             }
;             c += __shfl_xor(c, 32);
;             if (h == 0 && c) atomicAdd(&cnt[(31 - bit) * 32 + r], (unsigned)c);
;             __syncthreads();
;             const unsigned tot = cnt[(31 - bit) * 32 + r];
;             if (!done) { if (tot >= 256u) T = cand; if (tot == 256u) done = true; }
;             if (__ballot(!done) == 0ull) break;
;         }
;     }
.Lbs_c5:
	v_lshl_or_b32 v38, v43, 16, v42
	v_mov_b32_e32 v39, v44
	v_mov_b32_e32 v40, v38
	v_mov_b32_e32 v41, v39
	s_nop 1
	v_permlane32_swap_b32_e32 v38, v40
	v_permlane32_swap_b32_e32 v39, v41
	v_add_u32_e32 v38, v38, v40
	v_add_u32_e32 v39, v39, v41
	v_or_b32_e32 v22, v38, v39
	v_cmp_ne_u32_e32 vcc, 0, v22
	s_and_b64 vcc, vcc, s[58:59]
	s_and_saveexec_b64 s[54:55], vcc
	ds_add_u64 v48, v[38:39] offset:3328
	s_mov_b64 exec, s[54:55]
	s_waitcnt lgkmcnt(0)
	s_barrier
	ds_read_b64 v[40:41], v48 offset:3328
	s_waitcnt lgkmcnt(0)
	v_and_b32_e32 v22, s6, v40
	v_lshrrev_b32_e32 v23, 16, v40
	v_cmp_lt_u32_e64 s[48:49], s42, v22
	v_cmp_eq_u32_e32 vcc, s43, v22
	s_andn2_b64 s[50:51], s[48:49], s[44:45]
	s_or_b64 s[48:49], s[48:49], s[44:45]
	s_andn2_b64 s[52:53], exec, s[48:49]
	s_or_b64 s[44:45], s[44:45], vcc
	v_cndmask_b32_e64 v49, v41, v23, s[50:51]
	v_cndmask_b32_e64 v46, v44, v43, s[50:51]
	v_cndmask_b32_e64 v45, v45, v42, s[52:53]
	v_cmp_lt_u32_e64 s[48:49], s42, v49
	v_cmp_eq_u32_e32 vcc, s43, v49
	s_andn2_b64 s[0:1], s[48:49], s[44:45]
	s_or_b64 s[48:49], s[48:49], s[44:45]
	s_andn2_b64 s[22:23], exec, s[48:49]
	s_or_b64 s[44:45], s[44:45], vcc
	s_or_b64 s[46:47], s[46:47], s[50:51]
	s_or_b64 s[46:47], s[46:47], s[0:1]
	v_cndmask_b32_e64 v45, v45, v46, s[22:23]
	v_cndmask_b32_e64 v46, 0, v32, s[52:53]
	v_or_b32_e32 v28, v28, v46
	v_xor_b32_e32 v46, v24, v46
	v_cndmask_b32_e64 v24, v46, v32, s[50:51]
	v_and_b32_e32 v22, v24, v144
	v_cndmask_b32_e64 v46, 0, v22, s[22:23]
	v_or_b32_e32 v28, v28, v46
	v_xor_b32_e32 v46, v24, v46
	v_cndmask_b32_e64 v24, v46, v22, s[0:1]
	s_cmp_lt_i32 s41, 16
	s_cbranch_scc1 .Lbs_u5
	v_cndmask_b32_e64 v46, 0, v33, s[52:53]
	v_or_b32_e32 v29, v29, v46
	v_xor_b32_e32 v46, v25, v46
	v_cndmask_b32_e64 v25, v46, v33, s[50:51]
	v_and_b32_e32 v22, v25, v177
	v_cndmask_b32_e64 v46, 0, v22, s[22:23]
	v_or_b32_e32 v29, v29, v46
	v_xor_b32_e32 v46, v25, v46
	v_cndmask_b32_e64 v25, v46, v22, s[0:1]
	s_cmp_lt_i32 s41, 32
	s_cbranch_scc1 .Lbs_u5
	v_cndmask_b32_e64 v46, 0, v36, s[52:53]
	v_or_b32_e32 v30, v30, v46
	v_xor_b32_e32 v46, v26, v46
	v_cndmask_b32_e64 v26, v46, v36, s[50:51]
	v_and_b32_e32 v22, v26, v85
	v_cndmask_b32_e64 v46, 0, v22, s[22:23]
	v_or_b32_e32 v30, v30, v46
	v_xor_b32_e32 v46, v26, v46
	v_cndmask_b32_e64 v26, v46, v22, s[0:1]
	s_cmp_lt_i32 s41, 48
	s_cbranch_scc1 .Lbs_u5
	v_cndmask_b32_e64 v46, 0, v37, s[52:53]
	v_or_b32_e32 v31, v31, v46
	v_xor_b32_e32 v46, v27, v46
	v_cndmask_b32_e64 v27, v46, v37, s[50:51]
	v_and_b32_e32 v22, v27, v53
	v_cndmask_b32_e64 v46, 0, v22, s[22:23]
	v_or_b32_e32 v31, v31, v46
	v_xor_b32_e32 v46, v27, v46
	v_cndmask_b32_e64 v27, v46, v22, s[0:1]
.Lbs_u5:
	s_andn2_b64 s[48:49], exec, s[44:45]
	s_cbranch_scc0 .Lbs_end
	v_and_b32_e32 v32, v24, v141
	v_bcnt_u32_b32 v42, v32, v45
	v_and_b32_e32 v22, v24, v142
	v_and_b32_e32 v23, v32, v22
	v_bcnt_u32_b32 v43, v23, v45
	v_or_b32_e32 v23, v32, v22
	v_bcnt_u32_b32 v44, v23, v45
	s_cmp_lt_i32 s41, 16
	s_cbranch_scc1 .Lbs_c3
	v_and_b32_e32 v33, v25, v174
	v_bcnt_u32_b32 v42, v33, v42
	v_and_b32_e32 v22, v25, v175
	v_and_b32_e32 v23, v33, v22
	v_bcnt_u32_b32 v43, v23, v43
	v_or_b32_e32 v23, v33, v22
	v_bcnt_u32_b32 v44, v23, v44
	s_cmp_lt_i32 s41, 32
	s_cbranch_scc1 .Lbs_c3
	v_and_b32_e32 v36, v26, v82
	v_bcnt_u32_b32 v42, v36, v42
	v_and_b32_e32 v22, v26, v83
	v_and_b32_e32 v23, v36, v22
	v_bcnt_u32_b32 v43, v23, v43
	v_or_b32_e32 v23, v36, v22
	v_bcnt_u32_b32 v44, v23, v44
	s_cmp_lt_i32 s41, 48
	s_cbranch_scc1 .Lbs_c3
	v_and_b32_e32 v37, v27, v50
	v_bcnt_u32_b32 v42, v37, v42
	v_and_b32_e32 v22, v27, v51
	v_and_b32_e32 v23, v37, v22
	v_bcnt_u32_b32 v43, v23, v43
	v_or_b32_e32 v23, v37, v22
	v_bcnt_u32_b32 v44, v23, v44
.Lbs_c3:
	v_lshl_or_b32 v38, v43, 16, v42
	v_mov_b32_e32 v39, v44
	v_mov_b32_e32 v40, v38
	v_mov_b32_e32 v41, v39
	s_nop 1
	v_permlane32_swap_b32_e32 v38, v40
	v_permlane32_swap_b32_e32 v39, v41
	v_add_u32_e32 v38, v38, v40
	v_add_u32_e32 v39, v39, v41
	v_or_b32_e32 v22, v38, v39
	v_cmp_ne_u32_e32 vcc, 0, v22
	s_and_b64 vcc, vcc, s[58:59]
	s_and_saveexec_b64 s[54:55], vcc
	ds_add_u64 v48, v[38:39] offset:3584
	s_mov_b64 exec, s[54:55]
	s_waitcnt lgkmcnt(0)
	s_barrier
	ds_read_b64 v[40:41], v48 offset:3584
	s_waitcnt lgkmcnt(0)
	v_and_b32_e32 v22, s6, v40
	v_lshrrev_b32_e32 v23, 16, v40
	v_cmp_lt_u32_e64 s[48:49], s42, v22
	v_cmp_eq_u32_e32 vcc, s43, v22
	s_andn2_b64 s[50:51], s[48:49], s[44:45]
	s_or_b64 s[48:49], s[48:49], s[44:45]
	s_andn2_b64 s[52:53], exec, s[48:49]
	s_or_b64 s[44:45], s[44:45], vcc
	v_cndmask_b32_e64 v49, v41, v23, s[50:51]
	v_cndmask_b32_e64 v46, v44, v43, s[50:51]
	v_cndmask_b32_e64 v45, v45, v42, s[52:53]
	v_cmp_lt_u32_e64 s[48:49], s42, v49
	v_cmp_eq_u32_e32 vcc, s43, v49
	s_andn2_b64 s[0:1], s[48:49], s[44:45]
	s_or_b64 s[48:49], s[48:49], s[44:45]
	s_andn2_b64 s[22:23], exec, s[48:49]
	s_or_b64 s[44:45], s[44:45], vcc
	s_or_b64 s[46:47], s[46:47], s[50:51]
	s_or_b64 s[46:47], s[46:47], s[0:1]
	v_cndmask_b32_e64 v45, v45, v46, s[22:23]
	v_cndmask_b32_e64 v46, 0, v32, s[52:53]
	v_or_b32_e32 v28, v28, v46
	v_xor_b32_e32 v46, v24, v46
	v_cndmask_b32_e64 v24, v46, v32, s[50:51]
	v_and_b32_e32 v22, v24, v142
	v_cndmask_b32_e64 v46, 0, v22, s[22:23]
	v_or_b32_e32 v28, v28, v46
	v_xor_b32_e32 v46, v24, v46
	v_cndmask_b32_e64 v24, v46, v22, s[0:1]
	s_cmp_lt_i32 s41, 16
	s_cbranch_scc1 .Lbs_u3
	v_cndmask_b32_e64 v46, 0, v33, s[52:53]
	v_or_b32_e32 v29, v29, v46
	v_xor_b32_e32 v46, v25, v46
	v_cndmask_b32_e64 v25, v46, v33, s[50:51]
	v_and_b32_e32 v22, v25, v175
	v_cndmask_b32_e64 v46, 0, v22, s[22:23]
	v_or_b32_e32 v29, v29, v46
	v_xor_b32_e32 v46, v25, v46
	v_cndmask_b32_e64 v25, v46, v22, s[0:1]
	s_cmp_lt_i32 s41, 32
	s_cbranch_scc1 .Lbs_u3
	v_cndmask_b32_e64 v46, 0, v36, s[52:53]
	v_or_b32_e32 v30, v30, v46
	v_xor_b32_e32 v46, v26, v46
	v_cndmask_b32_e64 v26, v46, v36, s[50:51]
	v_and_b32_e32 v22, v26, v83
	v_cndmask_b32_e64 v46, 0, v22, s[22:23]
	v_or_b32_e32 v30, v30, v46
	v_xor_b32_e32 v46, v26, v46
	v_cndmask_b32_e64 v26, v46, v22, s[0:1]
	s_cmp_lt_i32 s41, 48
	s_cbranch_scc1 .Lbs_u3
	v_cndmask_b32_e64 v46, 0, v37, s[52:53]
	v_or_b32_e32 v31, v31, v46
	v_xor_b32_e32 v46, v27, v46
	v_cndmask_b32_e64 v27, v46, v37, s[50:51]
	v_and_b32_e32 v22, v27, v51
	v_cndmask_b32_e64 v46, 0, v22, s[22:23]
	v_or_b32_e32 v31, v31, v46
	v_xor_b32_e32 v46, v27, v46
	v_cndmask_b32_e64 v27, v46, v22, s[0:1]
; DI void a1_task(unsigned char* shm, const bf16_t* prm, const bf16_t* prt, unsigned* mask, int b, int qt, const int tid) {
;     ...
;             const unsigned cand = T | (1u << bit);
;             int c = 0;
; #pragma unroll
;             for (int jt = 0; jt < 8; ++jt) {
;                 if (jt < nheld) {
; #pragma unroll
;                     for (int i = 0; i < 16; ++i) c += (key[jt][i] >= cand) ? 1 : 0;
;                 }
;             }
;             c += __shfl_xor(c, 32);
;             if (h == 0 && c) atomicAdd(&cnt[(31 - bit) * 32 + r], (unsigned)c);
;             __syncthreads();
;             const unsigned tot = cnt[(31 - bit) * 32 + r];
;             if (!done) { if (tot >= 256u) T = cand; if (tot == 256u) done = true; }
;             if (__ballot(!done) == 0ull) break;
;         }
;     }
;     if (T < 1u) T = 1u;
; #pragma unroll
;     for (int jt = 0; jt < 8; ++jt) {
;         const int kt = wid + 8 * jt;
;         if (kt <= qt) {
;             unsigned part = 0u;
; #pragma unroll
;             for (int i = 0; i < 16; ++i) part |= (key[jt][i] >= T ? 1u : 0u) << (16 * (i >> 3) + 8 * h + (i & 7));
;             part |= (unsigned)__shfl_xor((int)part, 32);
;             if (h == 0) mask[(size_t)(tok0 + t0 + r) * 64 + kt] = part;
;         }
;     }
.Lbs_u3:
	s_andn2_b64 s[48:49], exec, s[44:45]
	s_cbranch_scc0 .Lbs_end
	v_and_b32_e32 v32, v24, v18
	v_bcnt_u32_b32 v42, v32, v45
	v_and_b32_e32 v22, v24, v156
	v_and_b32_e32 v23, v32, v22
	v_bcnt_u32_b32 v43, v23, v45
	v_or_b32_e32 v23, v32, v22
	v_bcnt_u32_b32 v44, v23, v45
	s_cmp_lt_i32 s41, 16
	s_cbranch_scc1 .Lbs_c1
	v_and_b32_e32 v33, v25, v19
	v_bcnt_u32_b32 v42, v33, v42
	v_and_b32_e32 v22, v25, v188
	v_and_b32_e32 v23, v33, v22
	v_bcnt_u32_b32 v43, v23, v43
	v_or_b32_e32 v23, v33, v22
	v_bcnt_u32_b32 v44, v23, v44
	s_cmp_lt_i32 s41, 32
	s_cbranch_scc1 .Lbs_c1
	v_and_b32_e32 v36, v26, v20
	v_bcnt_u32_b32 v42, v36, v42
	v_and_b32_e32 v22, v26, v229
	v_and_b32_e32 v23, v36, v22
	v_bcnt_u32_b32 v43, v23, v43
	v_or_b32_e32 v23, v36, v22
	v_bcnt_u32_b32 v44, v23, v44
	s_cmp_lt_i32 s41, 48
	s_cbranch_scc1 .Lbs_c1
	v_and_b32_e32 v37, v27, v21
	v_bcnt_u32_b32 v42, v37, v42
	v_and_b32_e32 v22, v27, v64
	v_and_b32_e32 v23, v37, v22
	v_bcnt_u32_b32 v43, v23, v43
	v_or_b32_e32 v23, v37, v22
	v_bcnt_u32_b32 v44, v23, v44
.Lbs_c1:
	v_lshl_or_b32 v38, v43, 16, v42
	v_mov_b32_e32 v39, v44
	v_mov_b32_e32 v40, v38
	v_mov_b32_e32 v41, v39
	s_nop 1
	v_permlane32_swap_b32_e32 v38, v40
	v_permlane32_swap_b32_e32 v39, v41
	v_add_u32_e32 v38, v38, v40
	v_add_u32_e32 v39, v39, v41
	v_or_b32_e32 v22, v38, v39
	v_cmp_ne_u32_e32 vcc, 0, v22
	s_and_b64 vcc, vcc, s[58:59]
	s_and_saveexec_b64 s[54:55], vcc
	ds_add_u64 v48, v[38:39] offset:3840
	s_mov_b64 exec, s[54:55]
	s_waitcnt lgkmcnt(0)
	s_barrier
	ds_read_b64 v[40:41], v48 offset:3840
	s_waitcnt lgkmcnt(0)
	v_and_b32_e32 v22, s6, v40
	v_lshrrev_b32_e32 v23, 16, v40
	v_cmp_lt_u32_e64 s[48:49], s42, v22
	v_cmp_eq_u32_e32 vcc, s43, v22
	s_andn2_b64 s[50:51], s[48:49], s[44:45]
	s_or_b64 s[48:49], s[48:49], s[44:45]
	s_andn2_b64 s[52:53], exec, s[48:49]
	s_or_b64 s[44:45], s[44:45], vcc
	v_cndmask_b32_e64 v49, v41, v23, s[50:51]
	v_cndmask_b32_e64 v46, v44, v43, s[50:51]
	v_cndmask_b32_e64 v45, v45, v42, s[52:53]
	v_cmp_lt_u32_e64 s[48:49], s42, v49
	v_cmp_eq_u32_e32 vcc, s43, v49
	s_andn2_b64 s[0:1], s[48:49], s[44:45]
	s_or_b64 s[48:49], s[48:49], s[44:45]
	s_andn2_b64 s[22:23], exec, s[48:49]
	s_or_b64 s[44:45], s[44:45], vcc
	s_or_b64 s[46:47], s[46:47], s[50:51]
	s_or_b64 s[46:47], s[46:47], s[0:1]
	v_cndmask_b32_e64 v45, v45, v46, s[22:23]
	v_cndmask_b32_e64 v46, 0, v32, s[52:53]
	v_or_b32_e32 v28, v28, v46
	v_xor_b32_e32 v46, v24, v46
	v_cndmask_b32_e64 v24, v46, v32, s[50:51]
	v_and_b32_e32 v22, v24, v156
	v_cndmask_b32_e64 v46, 0, v22, s[22:23]
	v_or_b32_e32 v28, v28, v46
	v_xor_b32_e32 v46, v24, v46
	v_cndmask_b32_e64 v24, v46, v22, s[0:1]
	s_cmp_lt_i32 s41, 16
	s_cbranch_scc1 .Lbs_u1
	v_cndmask_b32_e64 v46, 0, v33, s[52:53]
	v_or_b32_e32 v29, v29, v46
	v_xor_b32_e32 v46, v25, v46
	v_cndmask_b32_e64 v25, v46, v33, s[50:51]
	v_and_b32_e32 v22, v25, v188
	v_cndmask_b32_e64 v46, 0, v22, s[22:23]
	v_or_b32_e32 v29, v29, v46
	v_xor_b32_e32 v46, v25, v46
	v_cndmask_b32_e64 v25, v46, v22, s[0:1]
	s_cmp_lt_i32 s41, 32
	s_cbranch_scc1 .Lbs_u1
	v_cndmask_b32_e64 v46, 0, v36, s[52:53]
	v_or_b32_e32 v30, v30, v46
	v_xor_b32_e32 v46, v26, v46
	v_cndmask_b32_e64 v26, v46, v36, s[50:51]
	v_and_b32_e32 v22, v26, v229
	v_cndmask_b32_e64 v46, 0, v22, s[22:23]
	v_or_b32_e32 v30, v30, v46
	v_xor_b32_e32 v46, v26, v46
	v_cndmask_b32_e64 v26, v46, v22, s[0:1]
	s_cmp_lt_i32 s41, 48
	s_cbranch_scc1 .Lbs_u1
	v_cndmask_b32_e64 v46, 0, v37, s[52:53]
	v_or_b32_e32 v31, v31, v46
	v_xor_b32_e32 v46, v27, v46
	v_cndmask_b32_e64 v27, v46, v37, s[50:51]
	v_and_b32_e32 v22, v27, v64
	v_cndmask_b32_e64 v46, 0, v22, s[22:23]
	v_or_b32_e32 v31, v31, v46
	v_xor_b32_e32 v46, v27, v46
	v_cndmask_b32_e64 v27, v46, v22, s[0:1]
.Lbs_u1:
.Lbs_end:
	v_readlane_b32 s0, v255, 37
	s_mov_b32 s42, 0x5010400
	s_mov_b32 s43, 0x7030602
	v_or_b32_e32 v2, s0, v100
	v_ashrrev_i32_e32 v3, 31, v2
	v_readlane_b32 s0, v251, 27
	v_lshlrev_b64 v[2:3], 8, v[2:3]
	v_readlane_b32 s1, v251, 28
	v_readlane_b32 s6, v255, 40
	s_nop 1
	v_lshl_add_u64 v[2:3], s[0:1], 0, v[2:3]
	s_lshl_b32 s6, s6, 2
	s_mov_b32 s7, 0
	v_lshl_add_u64 v[2:3], s[6:7], 0, v[2:3]
	v_cndmask_b32_e64 v46, 0, v24, s[46:47]
	v_or_b32_e32 v46, v28, v46
	v_mov_b32_e32 v38, v46
	s_nop 1
	v_permlane32_swap_b32_e32 v38, v46
	v_perm_b32 v39, v46, v38, s42
	v_perm_b32 v40, v46, v38, s43
	s_mov_b64 exec, s[58:59]
	global_store_dword v[2:3], v39, off
	s_cmp_lt_i32 s41, 8
	s_cbranch_scc1 .Lbs_o0
	global_store_dword v[2:3], v40, off offset:32
.Lbs_o0:
	s_mov_b64 exec, s[8:9]
	s_cmp_lt_i32 s41, 16
	s_cbranch_scc1 .Lbs_out
	v_cndmask_b32_e64 v46, 0, v25, s[46:47]
	v_or_b32_e32 v46, v29, v46
	v_mov_b32_e32 v38, v46
	s_nop 1
	v_permlane32_swap_b32_e32 v38, v46
	v_perm_b32 v39, v46, v38, s42
	v_perm_b32 v40, v46, v38, s43
	s_mov_b64 exec, s[58:59]
	global_store_dword v[2:3], v39, off offset:64
	s_cmp_lt_i32 s41, 24
	s_cbranch_scc1 .Lbs_o1
	global_store_dword v[2:3], v40, off offset:96
.Lbs_o1:
	s_mov_b64 exec, s[8:9]
	s_cmp_lt_i32 s41, 32
	s_cbranch_scc1 .Lbs_out
	v_cndmask_b32_e64 v46, 0, v26, s[46:47]
	v_or_b32_e32 v46, v30, v46
	v_mov_b32_e32 v38, v46
	s_nop 1
	v_permlane32_swap_b32_e32 v38, v46
	v_perm_b32 v39, v46, v38, s42
	v_perm_b32 v40, v46, v38, s43
	s_mov_b64 exec, s[58:59]
	global_store_dword v[2:3], v39, off offset:128
	s_cmp_lt_i32 s41, 40
	s_cbranch_scc1 .Lbs_o2
	global_store_dword v[2:3], v40, off offset:160
.Lbs_o2:
	s_mov_b64 exec, s[8:9]
	s_cmp_lt_i32 s41, 48
	s_cbranch_scc1 .Lbs_out
	v_cndmask_b32_e64 v46, 0, v27, s[46:47]
	v_or_b32_e32 v46, v31, v46
	v_mov_b32_e32 v38, v46
	s_nop 1
	v_permlane32_swap_b32_e32 v38, v46
	v_perm_b32 v39, v46, v38, s42
	v_perm_b32 v40, v46, v38, s43
	s_mov_b64 exec, s[58:59]
	global_store_dword v[2:3], v39, off offset:192
	s_cmp_lt_i32 s41, 56
	s_cbranch_scc1 .Lbs_o3
	global_store_dword v[2:3], v40, off offset:224
